# RMSNorm loops (P0 x-norm, P9, P14, final P17): per-row gain loads hoisted out of the row loops so the store ladder has no vmcnt(0) waits (counted waits in P0 loop adjusted)
# speedup vs baseline: 1.0105x; 1.0105x over previous
; __device__ __forceinline__ unsigned cvt_pk_bf16(float lo, float hi) { f32x2_c v = {lo, hi}; bf16x2_c r = __builtin_convertvector(v, bf16x2_c); return __builtin_bit_cast(unsigned, r); }
; __device__ __forceinline__ void rms_row2_bf16(const float* xa, const float* xb, const float* g, bf16_t* oa, bf16_t* ob, int lane) {
;     f32x4 va[8], vb[8]; float sa = 0.f, sb = 0.f;
; #pragma unroll
;     for (int j = 0; j < 8; ++j) { va[j] = __builtin_nontemporal_load((const f32x4*)xa + lane + 64 * j); vb[j] = __builtin_nontemporal_load((const f32x4*)xb + lane + 64 * j); }
; #pragma unroll
;     for (int j = 0; j < 8; ++j) { sa += (va[j][0] * va[j][0] + va[j][1] * va[j][1]) + (va[j][2] * va[j][2] + va[j][3] * va[j][3]); sb += (vb[j][0] * vb[j][0] + vb[j][1] * vb[j][1]) + (vb[j][2] * vb[j][2] + vb[j][3] * vb[j][3]); }
;     const float ra = rsqrtf(wave_sum(sa) * (1.f / D) + EPS), rb = rsqrtf(wave_sum(sb) * (1.f / D) + EPS);
; #pragma unroll
;     for (int j = 0; j < 8; ++j) { const f32x4 gg = ((const f32x4*)g)[lane + 64 * j]; u32x2 o;
;         o.x = cvt_pk_bf16(va[j][0] * ra * gg[0], va[j][1] * ra * gg[1]); o.y = cvt_pk_bf16(va[j][2] * ra * gg[2], va[j][3] * ra * gg[3]); __builtin_nontemporal_store(o, (u32x2*)oa + lane + 64 * j);
;         o.x = cvt_pk_bf16(vb[j][0] * rb * gg[0], vb[j][1] * rb * gg[1]); o.y = cvt_pk_bf16(vb[j][2] * rb * gg[2], vb[j][3] * rb * gg[3]); __builtin_nontemporal_store(o, (u32x2*)ob + lane + 64 * j); }
; }
; __device__ __forceinline__ void norm_all_bf16(const float* src, const float* g, bf16_t* dst, int gw, int NGW, int lane) {
;     int m = gw;
;     for (; m + NGW < T; m += 2 * NGW) rms_row2_bf16(src + (size_t)m * D, src + (size_t)(m + NGW) * D, g, dst + (size_t)m * D, dst + (size_t)(m + NGW) * D, lane);
.LBB0_80:
	s_add_i32 s0, s38, s36
	s_cmpk_gt_i32 s0, 0x7fff
	s_mov_b32 s4, s38
	s_cbranch_scc1 .LBB0_85
	v_mbcnt_lo_u32_b32 v1, -1, 0
	v_mbcnt_hi_u32_b32 v4, -1, v1
	v_and_b32_e32 v1, 64, v4
	v_add_u32_e32 v5, 64, v1
	v_xor_b32_e32 v1, 1, v4
	v_cmp_lt_i32_e32 vcc, v1, v5
	v_xor_b32_e32 v6, 2, v4
	v_readlane_b32 s48, v245, 3
	v_cndmask_b32_e32 v1, v4, v1, vcc
	v_cmp_lt_i32_e32 vcc, v6, v5
	v_lshlrev_b32_e32 v2, 4, v176
	v_mov_b32_e32 v3, 0
	v_cndmask_b32_e32 v6, v4, v6, vcc
	v_readlane_b32 s52, v245, 7
	v_readlane_b32 s53, v245, 8
	v_lshlrev_b32_e32 v71, 2, v6
	v_xor_b32_e32 v6, 4, v4
	v_cmp_lt_i32_e32 vcc, v6, v5
	v_lshl_add_u64 v[56:57], s[52:53], 0, v[2:3]
	s_mov_b64 s[4:5], 0x1400
	v_cndmask_b32_e32 v6, v4, v6, vcc
	v_lshl_add_u64 v[60:61], v[56:57], 0, s[4:5]
	s_mov_b64 s[4:5], 0x1800
	v_readlane_b32 s6, v245, 1
	v_lshlrev_b32_e32 v74, 2, v6
	v_xor_b32_e32 v6, 8, v4
	v_lshl_add_u64 v[62:63], v[56:57], 0, s[4:5]
	s_mov_b64 s[4:5], 0x1c00
	s_add_i32 s1, s83, s6
	v_cmp_lt_i32_e32 vcc, v6, v5
	v_lshl_add_u64 v[64:65], v[56:57], 0, s[4:5]
	s_lshl_b32 s4, s6, 4
	s_lshl_b32 s6, s1, 3
	s_lshl_b64 s[18:19], s[38:39], 13
	v_readlane_b32 s49, v245, 4
	v_cndmask_b32_e32 v6, v4, v6, vcc
	s_add_u32 s18, s48, s18
	v_lshlrev_b32_e32 v75, 2, v6
	v_xor_b32_e32 v6, 16, v4
	s_addc_u32 s19, s49, s19
	v_lshl_add_u64 v[52:53], s[48:49], 0, v[2:3]
	v_cmp_lt_i32_e32 vcc, v6, v5
	v_mov_b32_e32 v51, v3
	s_mov_b64 s[8:9], 0x1000
	v_lshl_add_u64 v[2:3], s[18:19], 0, v[2:3]
	s_ashr_i32 s5, s4, 31
	v_cndmask_b32_e32 v6, v4, v6, vcc
	v_lshl_add_u64 v[58:59], v[56:57], 0, s[8:9]
	v_lshl_add_u64 v[66:67], v[2:3], 0, s[8:9]
	s_lshl_b64 s[18:19], s[4:5], 13
	s_lshl_b64 s[8:9], s[38:39], 12
	v_lshlrev_b32_e32 v76, 2, v6
	v_xor_b32_e32 v6, 32, v4
	s_add_u32 s8, s92, s8
	v_cmp_lt_i32_e32 vcc, v6, v5
	s_addc_u32 s9, s93, s9
	v_readlane_b32 s7, v245, 2
	v_cndmask_b32_e32 v4, v4, v6, vcc
	v_lshl_add_u64 v[2:3], s[8:9], 0, v[50:51]
	s_mov_b64 s[8:9], 0xde00000
	v_lshlrev_b32_e32 v1, 2, v1
	v_lshlrev_b32_e32 v77, 2, v4
	v_lshl_add_u64 v[54:55], s[80:81], 0, v[50:51]
	v_lshl_add_u64 v[68:69], v[2:3], 0, s[8:9]
	s_lshl_b64 s[20:21], s[4:5], 12
	s_movk_i32 s5, 0x1000
	s_mov_b32 s22, 0x3a000000
	v_mov_b32_e32 v70, 0x358637bd
	s_mov_b32 s7, 0x800000
	s_mov_b32 s8, s82
	s_mov_b32 s9, s38
	v_readlane_b32 s50, v245, 5
	v_readlane_b32 s51, v245, 6
	v_readlane_b32 s54, v245, 9
	v_readlane_b32 s55, v245, 10
	v_readlane_b32 s56, v245, 11
	v_readlane_b32 s57, v245, 12
	v_readlane_b32 s58, v245, 13
	v_readlane_b32 s59, v245, 14
	v_readlane_b32 s60, v245, 15
	v_readlane_b32 s61, v245, 16
	v_readlane_b32 s62, v245, 17
	v_readlane_b32 s63, v245, 18
	global_load_dwordx4 v[138:141], v[56:57], off
	global_load_dwordx4 v[142:145], v[56:57], off offset:1024
	global_load_dwordx4 v[146:149], v[56:57], off offset:2048
	global_load_dwordx4 v[150:153], v[56:57], off offset:3072
	global_load_dwordx4 v[154:157], v[58:59], off
	global_load_dwordx4 v[158:161], v[60:61], off
	global_load_dwordx4 v[162:165], v[62:63], off
	global_load_dwordx4 v[166:169], v[64:65], off
.LBB0_82:
	global_load_dwordx4 v[30:33], v[66:67], off offset:-4096 nt
	global_load_dwordx4 v[26:29], v[66:67], off offset:-3072 nt
	global_load_dwordx4 v[22:25], v[66:67], off offset:-2048 nt
	global_load_dwordx4 v[10:13], v[66:67], off offset:1024 nt
	global_load_dwordx4 v[14:17], v[66:67], off nt
	global_load_dwordx4 v[18:21], v[66:67], off offset:-1024 nt
	global_load_dwordx4 v[2:5], v[66:67], off offset:3072 nt
	global_load_dwordx4 v[6:9], v[66:67], off offset:2048 nt
	s_ashr_i32 s1, s0, 31
	s_lshl_b64 s[24:25], s[0:1], 13
	v_lshl_add_u64 v[34:35], v[52:53], 0, s[24:25]
	global_load_dwordx4 v[82:85], v[34:35], off offset:2048 nt
	global_load_dwordx4 v[86:89], v[34:35], off nt
	global_load_dwordx4 v[90:93], v[34:35], off offset:1024 nt
	global_load_dwordx4 v[94:97], v[34:35], off offset:3072 nt
	v_add_co_u32_e32 v34, vcc, s5, v34
	s_lshl_b64 s[0:1], s[0:1], 12
	s_nop 0
	v_addc_co_u32_e32 v35, vcc, 0, v35, vcc
	global_load_dwordx4 v[42:45], v[34:35], off offset:1024 nt
	global_load_dwordx4 v[46:49], v[34:35], off nt
	global_load_dwordx4 v[38:41], v[34:35], off offset:2048 nt
	s_nop 0
	global_load_dwordx4 v[34:37], v[34:35], off offset:3072 nt
	v_lshl_add_u64 v[72:73], v[54:55], 0, s[0:1]
	s_add_i32 s9, s9, s4
	s_add_i32 s8, s8, s4
	v_lshl_add_u64 v[66:67], v[66:67], 0, s[18:19]
	s_waitcnt vmcnt(15)
	v_mov_b32_e32 v100, v31
	s_waitcnt vmcnt(14)
	v_mov_b32_e32 v101, v27
	v_mov_b32_e32 v104, v33
	v_mov_b32_e32 v105, v29
	s_waitcnt vmcnt(13)
	v_pk_mul_f32 v[106:107], v[24:25], v[24:25]
	v_pk_mul_f32 v[108:109], v[22:23], v[22:23]
	s_waitcnt vmcnt(12)
	v_pk_mul_f32 v[110:111], v[12:13], v[12:13]
	v_pk_mul_f32 v[112:113], v[10:11], v[10:11]
	s_waitcnt vmcnt(11)
	v_mul_f32_e32 v121, v17, v17
	s_waitcnt vmcnt(10)
	v_mul_f32_e32 v114, v19, v19
	v_mul_f32_e32 v116, v21, v21
	s_waitcnt vmcnt(8)
	v_mul_f32_e32 v118, v7, v7
	v_mul_f32_e32 v120, v9, v9
	v_mov_b32_e32 v98, v30
	v_mov_b32_e32 v99, v26
	v_mov_b32_e32 v102, v32
	v_mov_b32_e32 v103, v28
	v_mul_f32_e32 v51, v16, v16
	v_mul_f32_e32 v124, v4, v4
	v_mul_f32_e32 v125, v5, v5
	v_pk_mov_b32 v[122:123], v[108:109], v[106:107] op_sel:[1,0]
	v_mov_b32_e32 v109, v107
	v_pk_mov_b32 v[106:107], v[112:113], v[110:111] op_sel:[1,0]
	v_mov_b32_e32 v113, v111
	v_pk_mul_f32 v[100:101], v[100:101], v[100:101]
	v_pk_mul_f32 v[104:105], v[104:105], v[104:105]
	v_pk_fma_f32 v[110:111], v[18:19], v[18:19], v[114:115] op_sel_hi:[1,1,0]
	v_pk_fma_f32 v[114:115], v[20:21], v[20:21], v[116:117] op_sel_hi:[1,1,0]
	v_pk_fma_f32 v[116:117], v[6:7], v[6:7], v[118:119] op_sel_hi:[1,1,0]
	v_pk_fma_f32 v[118:119], v[8:9], v[8:9], v[120:121] op_sel_hi:[1,1,0]
	v_pk_fma_f32 v[98:99], v[98:99], v[98:99], v[100:101]
	v_pk_fma_f32 v[100:101], v[102:103], v[102:103], v[104:105]
	v_mov_b32_e32 v111, v51
	v_mov_b32_e32 v115, v121
	v_mov_b32_e32 v117, v124
	v_mov_b32_e32 v119, v125
	v_pk_add_f32 v[102:103], v[122:123], v[108:109]
	v_pk_add_f32 v[104:105], v[106:107], v[112:113]
	v_pk_add_f32 v[98:99], v[98:99], v[100:101]
	v_pk_add_f32 v[100:101], v[110:111], v[114:115]
	v_pk_add_f32 v[106:107], v[116:117], v[118:119]
	s_waitcnt vmcnt(7)
; __device__ __forceinline__ float wave_sum(float v) {
; #pragma unroll
;     for (int o = 1; o < 64; o <<= 1) v += __shfl_xor(v, o);
;     return v;
; __device__ __forceinline__ void rms_row2_bf16(const float* xa, const float* xb, const float* g, bf16_t* oa, bf16_t* ob, int lane) {
;     ...
;     for (int j = 0; j < 8; ++j) { sa += (va[j][0] * va[j][0] + va[j][1] * va[j][1]) + (va[j][2] * va[j][2] + va[j][3] * va[j][3]); sb += (vb[j][0] * vb[j][0] + vb[j][1] * vb[j][1]) + (vb[j][2] * vb[j][2] + vb[j][3] * vb[j][3]); }
;     const float ra = rsqrtf(wave_sum(sa) * (1.f / D) + EPS), rb = rsqrtf(wave_sum(sb) * (1.f / D) + EPS);
	v_pk_mul_f32 v[108:109], v[84:85], v[84:85]
	v_pk_mul_f32 v[110:111], v[82:83], v[82:83]
	s_waitcnt vmcnt(6)
	v_mov_b32_e32 v114, v87
	s_waitcnt vmcnt(5)
	v_mov_b32_e32 v115, v91
	v_mov_b32_e32 v118, v89
	v_mov_b32_e32 v119, v93
	v_mov_b32_e32 v112, v86
	v_mov_b32_e32 v113, v90
	v_mov_b32_e32 v116, v88
	v_mov_b32_e32 v117, v92
	v_pk_mov_b32 v[124:125], v[110:111], v[108:109] op_sel:[1,0]
	v_mov_b32_e32 v111, v109
	v_pk_mul_f32 v[108:109], v[114:115], v[114:115]
	v_pk_mul_f32 v[114:115], v[118:119], v[118:119]
	v_pk_fma_f32 v[108:109], v[112:113], v[112:113], v[108:109]
	v_pk_fma_f32 v[112:113], v[116:117], v[116:117], v[114:115]
	s_waitcnt vmcnt(4)
	v_mul_f32_e32 v120, v95, v95
	v_mul_f32_e32 v122, v97, v97
	v_pk_add_f32 v[110:111], v[124:125], v[110:111]
	v_pk_add_f32 v[108:109], v[108:109], v[112:113]
	v_mul_f32_e32 v128, v15, v15
	v_mul_f32_e32 v129, v14, v14
	v_pk_add_f32 v[102:103], v[102:103], v[102:103] op_sel:[0,1] op_sel_hi:[1,0]
	v_pk_add_f32 v[98:99], v[98:99], v[98:99] op_sel:[0,1] op_sel_hi:[1,0]
	v_pk_fma_f32 v[120:121], v[94:95], v[94:95], v[120:121] op_sel_hi:[1,1,0]
	v_pk_fma_f32 v[122:123], v[96:97], v[96:97], v[122:123] op_sel_hi:[1,1,0]
	s_waitcnt vmcnt(2)
	v_mul_f32_e32 v135, v47, v47
	v_mul_f32_e32 v136, v46, v46
	v_pk_add_f32 v[110:111], v[110:111], v[110:111] op_sel:[0,1] op_sel_hi:[1,0]
	v_pk_add_f32 v[108:109], v[108:109], v[108:109] op_sel:[0,1] op_sel_hi:[1,0]
	v_pk_mul_f32 v[118:119], v[44:45], v[44:45]
	v_pk_mul_f32 v[126:127], v[42:43], v[42:43]
	v_mov_b32_e32 v103, v128
	v_mul_f32_e32 v121, v48, v48
	v_mul_f32_e32 v123, v49, v49
	v_mov_b32_e32 v99, v129
	v_mov_b32_e32 v111, v135
	v_mov_b32_e32 v109, v136
	v_mul_f32_e32 v131, v3, v3
	v_pk_add_f32 v[104:105], v[104:105], v[104:105] op_sel:[0,1] op_sel_hi:[1,0]
	v_pk_mov_b32 v[114:115], v[126:127], v[118:119] op_sel:[1,0]
	v_mov_b32_e32 v127, v119
	v_pk_add_f32 v[98:99], v[98:99], v[102:103]
	v_pk_add_f32 v[102:103], v[120:121], v[122:123]
	v_pk_add_f32 v[108:109], v[108:109], v[110:111]
	s_waitcnt vmcnt(1)
	v_mul_f32_e32 v128, v39, v39
	v_mul_f32_e32 v130, v41, v41
	v_mov_b32_e32 v105, v131
	s_waitcnt vmcnt(0)
	v_mul_f32_e32 v131, v35, v35
	v_pk_add_f32 v[112:113], v[114:115], v[126:127]
	v_pk_add_f32 v[98:99], v[98:99], v[100:101]
	v_pk_add_f32 v[102:103], v[108:109], v[102:103]
	v_mul_f32_e32 v132, v2, v2
	v_mul_f32_e32 v133, v36, v36
	v_mul_f32_e32 v134, v37, v37
	v_mul_f32_e32 v137, v34, v34
	v_pk_fma_f32 v[116:117], v[38:39], v[38:39], v[128:129] op_sel_hi:[1,1,0]
	v_pk_fma_f32 v[118:119], v[40:41], v[40:41], v[130:131] op_sel_hi:[1,1,0]
	v_pk_add_f32 v[112:113], v[112:113], v[112:113] op_sel:[0,1] op_sel_hi:[1,0]
	v_pk_add_f32 v[98:99], v[98:99], v[98:99] op_sel:[0,1] op_sel_hi:[1,0]
	v_pk_add_f32 v[102:103], v[102:103], v[102:103] op_sel:[0,1] op_sel_hi:[1,0]
	v_mov_b32_e32 v117, v133
	v_mov_b32_e32 v119, v134
	v_mov_b32_e32 v113, v131
	v_mov_b32_e32 v99, v132
	v_mov_b32_e32 v103, v137
	v_pk_add_f32 v[100:101], v[116:117], v[118:119]
	v_pk_add_f32 v[98:99], v[98:99], v[104:105]
	v_pk_add_f32 v[102:103], v[102:103], v[112:113]
	v_pk_add_f32 v[98:99], v[98:99], v[106:107]
	v_pk_add_f32 v[100:101], v[102:103], v[100:101]
	v_mov_b32_e32 v105, v98
	v_mov_b32_e32 v104, v100
	v_mov_b32_e32 v98, v101
	v_pk_add_f32 v[98:99], v[104:105], v[98:99]
	ds_bpermute_b32 v101, v1, v99
	ds_bpermute_b32 v100, v1, v98
	s_waitcnt lgkmcnt(0)
	v_pk_add_f32 v[98:99], v[98:99], v[100:101]
	ds_bpermute_b32 v101, v71, v99
	ds_bpermute_b32 v100, v71, v98
	s_waitcnt lgkmcnt(0)
	v_pk_add_f32 v[98:99], v[98:99], v[100:101]
	ds_bpermute_b32 v101, v74, v99
	ds_bpermute_b32 v100, v74, v98
	s_waitcnt lgkmcnt(0)
	v_pk_add_f32 v[98:99], v[98:99], v[100:101]
	ds_bpermute_b32 v101, v75, v99
	ds_bpermute_b32 v100, v75, v98
	s_waitcnt lgkmcnt(0)
	v_pk_add_f32 v[98:99], v[98:99], v[100:101]
	ds_bpermute_b32 v101, v76, v99
	ds_bpermute_b32 v100, v76, v98
	s_waitcnt lgkmcnt(0)
	v_pk_add_f32 v[98:99], v[98:99], v[100:101]
	ds_bpermute_b32 v101, v77, v99
	ds_bpermute_b32 v100, v77, v98
	s_waitcnt lgkmcnt(0)
; __device__ __forceinline__ unsigned cvt_pk_bf16(float lo, float hi) { f32x2_c v = {lo, hi}; bf16x2_c r = __builtin_convertvector(v, bf16x2_c); return __builtin_bit_cast(unsigned, r); }
; __device__ __forceinline__ void rms_row2_bf16(const float* xa, const float* xb, const float* g, bf16_t* oa, bf16_t* ob, int lane) {
;     ...
;     const float ra = rsqrtf(wave_sum(sa) * (1.f / D) + EPS), rb = rsqrtf(wave_sum(sb) * (1.f / D) + EPS);
; #pragma unroll
;     for (int j = 0; j < 8; ++j) { const f32x4 gg = ((const f32x4*)g)[lane + 64 * j]; u32x2 o;
;         o.x = cvt_pk_bf16(va[j][0] * ra * gg[0], va[j][1] * ra * gg[1]); o.y = cvt_pk_bf16(va[j][2] * ra * gg[2], va[j][3] * ra * gg[3]); __builtin_nontemporal_store(o, (u32x2*)oa + lane + 64 * j);
;         o.x = cvt_pk_bf16(vb[j][0] * rb * gg[0], vb[j][1] * rb * gg[1]); o.y = cvt_pk_bf16(vb[j][2] * rb * gg[2], vb[j][3] * rb * gg[3]); __builtin_nontemporal_store(o, (u32x2*)ob + lane + 64 * j); }
	v_pk_add_f32 v[98:99], v[98:99], v[100:101]
	s_nop 0
	v_pk_fma_f32 v[98:99], v[98:99], s[22:23], v[70:71] op_sel_hi:[1,0,0]
	s_nop 0
	v_mul_f32_e32 v100, 0x4b800000, v99
	v_cmp_gt_f32_e64 s[0:1], s7, v99
	v_mul_f32_e32 v51, 0x4b800000, v98
	v_cmp_gt_f32_e32 vcc, s7, v98
	v_cndmask_b32_e64 v99, v99, v100, s[0:1]
	s_nop 0
	v_cndmask_b32_e32 v51, v98, v51, vcc
	v_rsq_f32_e32 v98, v99
	v_rsq_f32_e32 v51, v51
	v_mul_f32_e32 v99, 0x45800000, v98
	v_mul_f32_e32 v100, 0x45800000, v51
	v_cndmask_b32_e64 v98, v98, v99, s[0:1]
	v_cndmask_b32_e32 v100, v51, v100, vcc
	v_pk_mul_f32 v[30:31], v[30:31], v[98:99] op_sel_hi:[1,0]
	v_pk_mul_f32 v[32:33], v[32:33], v[98:99] op_sel_hi:[1,0]
	v_pk_mul_f32 v[86:87], v[86:87], v[100:101] op_sel_hi:[1,0]
	v_pk_mul_f32 v[88:89], v[88:89], v[100:101] op_sel_hi:[1,0]
	v_pk_mul_f32 v[30:31], v[138:139], v[30:31]
	v_pk_mul_f32 v[32:33], v[140:141], v[32:33]
	v_pk_mul_f32 v[78:79], v[138:139], v[86:87]
	v_pk_mul_f32 v[80:81], v[140:141], v[88:89]
	v_cvt_pk_bf16_f32 v30, v30, v31
	v_cvt_pk_bf16_f32 v31, v32, v33
	v_cvt_pk_bf16_f32 v32, v78, v79
	v_cvt_pk_bf16_f32 v33, v80, v81
	global_store_dwordx2 v[68:69], v[30:31], off nt
	global_store_dwordx2 v[72:73], v[32:33], off nt
	v_pk_mul_f32 v[26:27], v[26:27], v[98:99] op_sel_hi:[1,0]
	v_pk_mul_f32 v[28:29], v[28:29], v[98:99] op_sel_hi:[1,0]
	v_pk_mul_f32 v[78:79], v[90:91], v[100:101] op_sel_hi:[1,0]
	v_pk_mul_f32 v[80:81], v[92:93], v[100:101] op_sel_hi:[1,0]
	v_pk_mul_f32 v[22:23], v[22:23], v[98:99] op_sel_hi:[1,0]
	v_pk_mul_f32 v[24:25], v[24:25], v[98:99] op_sel_hi:[1,0]
	v_pk_mul_f32 v[18:19], v[18:19], v[98:99] op_sel_hi:[1,0]
	v_pk_mul_f32 v[20:21], v[20:21], v[98:99] op_sel_hi:[1,0]
	v_pk_mul_f32 v[14:15], v[14:15], v[98:99] op_sel_hi:[1,0]
	v_pk_mul_f32 v[16:17], v[16:17], v[98:99] op_sel_hi:[1,0]
	v_pk_mul_f32 v[10:11], v[10:11], v[98:99] op_sel_hi:[1,0]
	v_pk_mul_f32 v[12:13], v[12:13], v[98:99] op_sel_hi:[1,0]
	v_pk_mul_f32 v[6:7], v[6:7], v[98:99] op_sel_hi:[1,0]
	v_pk_mul_f32 v[8:9], v[8:9], v[98:99] op_sel_hi:[1,0]
	v_pk_mul_f32 v[2:3], v[2:3], v[98:99] op_sel_hi:[1,0]
	v_pk_mul_f32 v[4:5], v[4:5], v[98:99] op_sel_hi:[1,0]
	s_add_i32 s0, s9, s36
	s_add_i32 s1, s6, s8
	s_cmpk_gt_i32 s1, 0x7fff
	v_pk_mul_f32 v[26:27], v[142:143], v[26:27]
	v_pk_mul_f32 v[28:29], v[144:145], v[28:29]
	v_pk_mul_f32 v[30:31], v[142:143], v[78:79]
	v_pk_mul_f32 v[32:33], v[144:145], v[80:81]
	v_cvt_pk_bf16_f32 v26, v26, v27
	v_cvt_pk_bf16_f32 v27, v28, v29
	v_cvt_pk_bf16_f32 v28, v30, v31
	v_cvt_pk_bf16_f32 v29, v32, v33
	global_store_dwordx2 v[68:69], v[26:27], off offset:512 nt
	global_store_dwordx2 v[72:73], v[28:29], off offset:512 nt
	v_pk_mul_f32 v[30:31], v[82:83], v[100:101] op_sel_hi:[1,0]
	v_pk_mul_f32 v[32:33], v[84:85], v[100:101] op_sel_hi:[1,0]
	v_pk_mul_f32 v[22:23], v[22:23], v[146:147]
	v_pk_mul_f32 v[24:25], v[24:25], v[148:149]
	v_pk_mul_f32 v[26:27], v[146:147], v[30:31]
	v_pk_mul_f32 v[28:29], v[148:149], v[32:33]
	v_cvt_pk_bf16_f32 v22, v22, v23
	v_cvt_pk_bf16_f32 v23, v24, v25
	v_cvt_pk_bf16_f32 v24, v26, v27
	v_cvt_pk_bf16_f32 v25, v28, v29
	global_store_dwordx2 v[68:69], v[22:23], off offset:1024 nt
	global_store_dwordx2 v[72:73], v[24:25], off offset:1024 nt
	v_pk_mul_f32 v[26:27], v[94:95], v[100:101] op_sel_hi:[1,0]
	v_pk_mul_f32 v[28:29], v[96:97], v[100:101] op_sel_hi:[1,0]
	v_pk_mul_f32 v[18:19], v[18:19], v[150:151]
	v_pk_mul_f32 v[20:21], v[20:21], v[152:153]
	v_pk_mul_f32 v[22:23], v[26:27], v[150:151]
	v_pk_mul_f32 v[24:25], v[28:29], v[152:153]
	v_cvt_pk_bf16_f32 v18, v18, v19
	v_cvt_pk_bf16_f32 v19, v20, v21
	v_cvt_pk_bf16_f32 v20, v22, v23
	v_cvt_pk_bf16_f32 v21, v24, v25
	global_store_dwordx2 v[68:69], v[18:19], off offset:1536 nt
	global_store_dwordx2 v[72:73], v[20:21], off offset:1536 nt
	v_pk_mul_f32 v[22:23], v[46:47], v[100:101] op_sel_hi:[1,0]
	v_pk_mul_f32 v[24:25], v[48:49], v[100:101] op_sel_hi:[1,0]
	v_pk_mul_f32 v[14:15], v[14:15], v[154:155]
	v_pk_mul_f32 v[16:17], v[16:17], v[156:157]
	v_pk_mul_f32 v[18:19], v[22:23], v[154:155]
	v_pk_mul_f32 v[20:21], v[24:25], v[156:157]
	v_cvt_pk_bf16_f32 v14, v14, v15
	v_cvt_pk_bf16_f32 v15, v16, v17
	v_cvt_pk_bf16_f32 v16, v18, v19
	v_cvt_pk_bf16_f32 v17, v20, v21
	global_store_dwordx2 v[68:69], v[14:15], off offset:2048 nt
	global_store_dwordx2 v[72:73], v[16:17], off offset:2048 nt
	v_pk_mul_f32 v[18:19], v[42:43], v[100:101] op_sel_hi:[1,0]
	v_pk_mul_f32 v[20:21], v[44:45], v[100:101] op_sel_hi:[1,0]
	v_pk_mul_f32 v[10:11], v[10:11], v[158:159]
	v_pk_mul_f32 v[12:13], v[12:13], v[160:161]
	v_pk_mul_f32 v[14:15], v[18:19], v[158:159]
	v_pk_mul_f32 v[16:17], v[20:21], v[160:161]
	v_cvt_pk_bf16_f32 v10, v10, v11
	v_cvt_pk_bf16_f32 v11, v12, v13
	v_cvt_pk_bf16_f32 v12, v14, v15
	v_cvt_pk_bf16_f32 v13, v16, v17
	global_store_dwordx2 v[68:69], v[10:11], off offset:2560 nt
	global_store_dwordx2 v[72:73], v[12:13], off offset:2560 nt
	v_pk_mul_f32 v[14:15], v[38:39], v[100:101] op_sel_hi:[1,0]
	v_pk_mul_f32 v[16:17], v[40:41], v[100:101] op_sel_hi:[1,0]
	v_pk_mul_f32 v[6:7], v[6:7], v[162:163]
	v_pk_mul_f32 v[8:9], v[8:9], v[164:165]
	v_pk_mul_f32 v[10:11], v[14:15], v[162:163]
	v_pk_mul_f32 v[12:13], v[16:17], v[164:165]
	v_cvt_pk_bf16_f32 v6, v6, v7
	v_cvt_pk_bf16_f32 v7, v8, v9
	v_cvt_pk_bf16_f32 v8, v10, v11
	v_cvt_pk_bf16_f32 v9, v12, v13
	global_store_dwordx2 v[68:69], v[6:7], off offset:3072 nt
	global_store_dwordx2 v[72:73], v[8:9], off offset:3072 nt
	v_pk_mul_f32 v[10:11], v[34:35], v[100:101] op_sel_hi:[1,0]
	v_pk_mul_f32 v[12:13], v[36:37], v[100:101] op_sel_hi:[1,0]
	v_pk_mul_f32 v[2:3], v[2:3], v[166:167]
	v_pk_mul_f32 v[4:5], v[4:5], v[168:169]
	v_pk_mul_f32 v[6:7], v[10:11], v[166:167]
	v_pk_mul_f32 v[8:9], v[12:13], v[168:169]
	v_cvt_pk_bf16_f32 v2, v2, v3
	v_cvt_pk_bf16_f32 v3, v4, v5
	v_cvt_pk_bf16_f32 v4, v6, v7
	v_cvt_pk_bf16_f32 v5, v8, v9
	global_store_dwordx2 v[68:69], v[2:3], off offset:3584 nt
	global_store_dwordx2 v[72:73], v[4:5], off offset:3584 nt
	v_lshl_add_u64 v[68:69], v[68:69], 0, s[20:21]
	s_cbranch_scc0 .LBB0_82
	v_readlane_b32 s0, v245, 40
	v_readlane_b32 s48, v245, 24
	s_add_i32 s4, s0, s8
	v_readlane_b32 s49, v245, 25
	v_readlane_b32 s50, v245, 26
	v_readlane_b32 s51, v245, 27
	v_readlane_b32 s52, v245, 28
	v_readlane_b32 s53, v245, 29
	v_readlane_b32 s54, v245, 30
	v_readlane_b32 s55, v245, 31
	v_readlane_b32 s56, v245, 32
	v_readlane_b32 s57, v245, 33
	v_readlane_b32 s58, v245, 34
	v_readlane_b32 s59, v245, 35
	v_readlane_b32 s60, v245, 36
	v_readlane_b32 s61, v245, 37
	v_readlane_b32 s62, v245, 38
	v_readlane_b32 s63, v245, 39
	s_cmpk_gt_i32 s4, 0x7fff
	s_cbranch_scc0 .LBB0_86

; __device__ __forceinline__ unsigned cvt_pk_bf16(float lo, float hi) { f32x2_c v = {lo, hi}; bf16x2_c r = __builtin_convertvector(v, bf16x2_c); return __builtin_bit_cast(unsigned, r); }
; __device__ __forceinline__ void rms_row2_bf16(const float* xa, const float* xb, const float* g, bf16_t* oa, bf16_t* ob, int lane) {
;     f32x4 va[8], vb[8]; float sa = 0.f, sb = 0.f;
; #pragma unroll
;     for (int j = 0; j < 8; ++j) { va[j] = __builtin_nontemporal_load((const f32x4*)xa + lane + 64 * j); vb[j] = __builtin_nontemporal_load((const f32x4*)xb + lane + 64 * j); }
; #pragma unroll
;     for (int j = 0; j < 8; ++j) { sa += (va[j][0] * va[j][0] + va[j][1] * va[j][1]) + (va[j][2] * va[j][2] + va[j][3] * va[j][3]); sb += (vb[j][0] * vb[j][0] + vb[j][1] * vb[j][1]) + (vb[j][2] * vb[j][2] + vb[j][3] * vb[j][3]); }
;     const float ra = rsqrtf(wave_sum(sa) * (1.f / D) + EPS), rb = rsqrtf(wave_sum(sb) * (1.f / D) + EPS);
; #pragma unroll
;     for (int j = 0; j < 8; ++j) { const f32x4 gg = ((const f32x4*)g)[lane + 64 * j]; u32x2 o;
;         o.x = cvt_pk_bf16(va[j][0] * ra * gg[0], va[j][1] * ra * gg[1]); o.y = cvt_pk_bf16(va[j][2] * ra * gg[2], va[j][3] * ra * gg[3]); __builtin_nontemporal_store(o, (u32x2*)oa + lane + 64 * j);
;         o.x = cvt_pk_bf16(vb[j][0] * rb * gg[0], vb[j][1] * rb * gg[1]); o.y = cvt_pk_bf16(vb[j][2] * rb * gg[2], vb[j][3] * rb * gg[3]); __builtin_nontemporal_store(o, (u32x2*)ob + lane + 64 * j); }
; }
; __device__ __forceinline__ void norm_all_bf16(const float* src, const float* g, bf16_t* dst, int gw, int NGW, int lane) {
;     int m = gw;
;     for (; m + NGW < T; m += 2 * NGW) rms_row2_bf16(src + (size_t)m * D, src + (size_t)(m + NGW) * D, g, dst + (size_t)m * D, dst + (size_t)(m + NGW) * D, lane);
.LBB0_1055:
	v_readlane_b32 s0, v244, 9
	v_readlane_b32 s2, v244, 41
	s_add_i32 s14, s0, s2
	s_cmpk_gt_i32 s14, 0x7fff
	v_readlane_b32 s1, v244, 10
	v_readlane_b32 s3, v244, 42
	s_cbranch_scc1 .LBB0_1059
	v_mbcnt_lo_u32_b32 v2, -1, 0
	v_mbcnt_hi_u32_b32 v2, -1, v2
	v_and_b32_e32 v3, 64, v2
	v_add_u32_e32 v3, 64, v3
	v_xor_b32_e32 v4, 1, v2
	v_cmp_lt_i32_e32 vcc, v4, v3
	v_readlane_b32 s16, v245, 49
	v_lshlrev_b32_e32 v0, 4, v176
	v_cndmask_b32_e32 v4, v2, v4, vcc
	v_lshlrev_b32_e32 v71, 2, v4
	v_xor_b32_e32 v4, 2, v2
	v_cmp_lt_i32_e32 vcc, v4, v3
	v_mov_b32_e32 v1, 0
	v_readlane_b32 s24, v245, 57
	v_cndmask_b32_e32 v4, v2, v4, vcc
	v_lshlrev_b32_e32 v74, 2, v4
	v_xor_b32_e32 v4, 4, v2
	v_cmp_lt_i32_e32 vcc, v4, v3
	v_readlane_b32 s25, v245, 58
	s_mov_b64 s[2:3], 0x1400
	v_cndmask_b32_e32 v4, v2, v4, vcc
	v_lshl_add_u64 v[56:57], s[24:25], 0, v[0:1]
	v_lshlrev_b32_e32 v75, 2, v4
	v_xor_b32_e32 v4, 8, v2
	v_lshl_add_u64 v[60:61], v[56:57], 0, s[2:3]
	s_mov_b64 s[2:3], 0x1800
	v_readlane_b32 s8, v245, 1
	v_cmp_lt_i32_e32 vcc, v4, v3
	v_lshl_add_u64 v[62:63], v[56:57], 0, s[2:3]
	s_mov_b64 s[2:3], 0x1c00
	v_readlane_b32 s9, v245, 2
	v_cndmask_b32_e32 v4, v2, v4, vcc
	v_readlane_b32 s18, v245, 51
	v_readlane_b32 s19, v245, 52
	v_lshl_add_u64 v[64:65], v[56:57], 0, s[2:3]
	s_lshl_b32 s2, s8, 4
	s_add_i32 s3, s83, s8
	v_readlane_b32 s8, v244, 9
	v_lshlrev_b32_e32 v76, 2, v4
	v_xor_b32_e32 v4, 16, v2
	v_readlane_b32 s9, v244, 10
	s_mov_b32 s18, s8
	s_ashr_i32 s19, s8, 31
	v_cmp_lt_i32_e32 vcc, v4, v3
	s_lshl_b32 s13, s3, 3
	s_lshl_b64 s[8:9], s[18:19], 13
	v_cndmask_b32_e32 v4, v2, v4, vcc
	s_add_u32 s8, s86, s8
	v_lshlrev_b32_e32 v77, 2, v4
	v_xor_b32_e32 v4, 32, v2
	s_addc_u32 s9, s87, s9
	v_lshl_add_u64 v[52:53], s[86:87], 0, v[0:1]
	v_cmp_lt_i32_e32 vcc, v4, v3
	v_mov_b32_e32 v3, v1
	s_mov_b64 s[0:1], 0x1000
	v_lshl_add_u64 v[0:1], s[8:9], 0, v[0:1]
	s_ashr_i32 s3, s2, 31
	v_lshl_add_u64 v[58:59], v[56:57], 0, s[0:1]
	v_lshl_add_u64 v[66:67], v[0:1], 0, s[0:1]
	s_lshl_b64 s[8:9], s[2:3], 13
	s_lshl_b64 s[0:1], s[18:19], 12
	v_cndmask_b32_e32 v2, v2, v4, vcc
	s_add_u32 s0, s88, s0
	v_lshlrev_b32_e32 v78, 2, v2
	v_lshlrev_b32_e32 v2, 3, v176
	s_addc_u32 s1, s89, s1
	v_lshl_add_u64 v[0:1], s[0:1], 0, v[2:3]
	s_mov_b64 s[0:1], 0xde00000
	v_lshl_add_u64 v[68:69], v[0:1], 0, s[0:1]
	s_mov_b32 s0, s18
	v_readlane_b32 s31, v244, 0
	v_writelane_b32 v244, s0, 9
	v_readlane_b32 s17, v245, 50
	v_readlane_b32 s20, v245, 53
	v_readlane_b32 s21, v245, 54
	v_writelane_b32 v244, s1, 10
	v_lshl_add_u64 v[54:55], s[80:81], 0, v[2:3]
	s_lshl_b64 s[10:11], s[2:3], 12
	s_movk_i32 s3, 0x1000
	s_mov_b32 s12, 0x3a000000
	v_mov_b32_e32 v70, 0x358637bd
	s_mov_b32 s16, 0x800000
	s_mov_b32 s17, s82
	v_readlane_b32 s20, v244, 41
	v_readlane_b32 s22, v245, 55
	v_readlane_b32 s23, v245, 56
	v_readlane_b32 s26, v245, 59
	v_readlane_b32 s27, v245, 60
	v_readlane_b32 s28, v245, 61
	v_readlane_b32 s29, v245, 62
	v_readlane_b32 s30, v245, 63
	v_readlane_b32 s21, v244, 42
	global_load_dwordx4 v[138:141], v[56:57], off
	global_load_dwordx4 v[142:145], v[56:57], off offset:1024
	global_load_dwordx4 v[146:149], v[56:57], off offset:2048
	global_load_dwordx4 v[150:153], v[56:57], off offset:3072
	global_load_dwordx4 v[154:157], v[58:59], off
	global_load_dwordx4 v[158:161], v[60:61], off
	global_load_dwordx4 v[162:165], v[62:63], off
	global_load_dwordx4 v[168:171], v[64:65], off
.LBB0_1057:
	global_load_dwordx4 v[28:31], v[66:67], off offset:-4096 nt
	global_load_dwordx4 v[24:27], v[66:67], off offset:-3072 nt
	global_load_dwordx4 v[20:23], v[66:67], off offset:-2048 nt
	global_load_dwordx4 v[12:15], v[66:67], off nt
	global_load_dwordx4 v[16:19], v[66:67], off offset:-1024 nt
	global_load_dwordx4 v[8:11], v[66:67], off offset:1024 nt
	global_load_dwordx4 v[0:3], v[66:67], off offset:3072 nt
	global_load_dwordx4 v[4:7], v[66:67], off offset:2048 nt
	s_ashr_i32 s15, s14, 31
	s_lshl_b64 s[0:1], s[14:15], 13
	v_lshl_add_u64 v[32:33], v[52:53], 0, s[0:1]
	global_load_dwordx4 v[84:87], v[32:33], off nt
	global_load_dwordx4 v[88:91], v[32:33], off offset:1024 nt
	global_load_dwordx4 v[92:95], v[32:33], off offset:2048 nt
	global_load_dwordx4 v[48:51], v[32:33], off offset:3072 nt
	v_add_co_u32_e32 v36, vcc, s3, v32
	s_lshl_b64 s[14:15], s[14:15], 12
	s_nop 0
	v_addc_co_u32_e32 v37, vcc, 0, v33, vcc
	global_load_dwordx4 v[44:47], v[36:37], off nt
	global_load_dwordx4 v[40:43], v[36:37], off offset:1024 nt
	global_load_dwordx4 v[32:35], v[36:37], off offset:3072 nt
	s_nop 0
	global_load_dwordx4 v[36:39], v[36:37], off offset:2048 nt
	v_lshl_add_u64 v[72:73], v[54:55], 0, s[14:15]
	s_add_i32 s18, s18, s2
	s_add_i32 s17, s17, s2
	s_add_i32 s14, s18, s20
	v_lshl_add_u64 v[66:67], v[66:67], 0, s[8:9]
	s_waitcnt vmcnt(0)
; __device__ __forceinline__ float wave_sum(float v) {
; #pragma unroll
;     for (int o = 1; o < 64; o <<= 1) v += __shfl_xor(v, o);
;     return v;
; __device__ __forceinline__ void rms_row2_bf16(const float* xa, const float* xb, const float* g, bf16_t* oa, bf16_t* ob, int lane) {
;     ...
;     for (int j = 0; j < 8; ++j) { sa += (va[j][0] * va[j][0] + va[j][1] * va[j][1]) + (va[j][2] * va[j][2] + va[j][3] * va[j][3]); sb += (vb[j][0] * vb[j][0] + vb[j][1] * vb[j][1]) + (vb[j][2] * vb[j][2] + vb[j][3] * vb[j][3]); }
;     const float ra = rsqrtf(wave_sum(sa) * (1.f / D) + EPS), rb = rsqrtf(wave_sum(sb) * (1.f / D) + EPS);
	v_mov_b32_e32 v98, v29
	v_mov_b32_e32 v99, v25
	v_mov_b32_e32 v102, v31
	v_mov_b32_e32 v103, v27
	v_pk_mul_f32 v[104:105], v[22:23], v[22:23]
	v_pk_mul_f32 v[106:107], v[20:21], v[20:21]
	v_mul_f32_e32 v108, v17, v17
	v_mul_f32_e32 v110, v19, v19
	v_pk_mul_f32 v[112:113], v[10:11], v[10:11]
	v_pk_mul_f32 v[114:115], v[8:9], v[8:9]
	v_mov_b32_e32 v96, v28
	v_mov_b32_e32 v97, v24
	v_mov_b32_e32 v100, v30
	v_mov_b32_e32 v101, v26
	v_mul_f32_e32 v119, v14, v14
	v_mul_f32_e32 v116, v5, v5
	v_mul_f32_e32 v118, v7, v7
	v_pk_mul_f32 v[98:99], v[98:99], v[98:99]
	v_pk_mul_f32 v[102:103], v[102:103], v[102:103]
	v_pk_mov_b32 v[120:121], v[106:107], v[104:105] op_sel:[1,0]
	v_mov_b32_e32 v107, v105
	v_pk_fma_f32 v[104:105], v[16:17], v[16:17], v[108:109] op_sel_hi:[1,1,0]
	v_pk_fma_f32 v[108:109], v[18:19], v[18:19], v[110:111] op_sel_hi:[1,1,0]
	v_pk_mov_b32 v[110:111], v[114:115], v[112:113] op_sel:[1,0]
	v_mov_b32_e32 v115, v113
	v_mul_f32_e32 v124, v2, v2
	v_mul_f32_e32 v125, v3, v3
	v_pk_fma_f32 v[112:113], v[4:5], v[4:5], v[116:117] op_sel_hi:[1,1,0]
	v_pk_fma_f32 v[116:117], v[6:7], v[6:7], v[118:119] op_sel_hi:[1,1,0]
	v_pk_fma_f32 v[96:97], v[96:97], v[96:97], v[98:99]
	v_pk_fma_f32 v[98:99], v[100:101], v[100:101], v[102:103]
	v_pk_add_f32 v[100:101], v[120:121], v[106:107]
	v_pk_add_f32 v[102:103], v[110:111], v[114:115]
	v_mov_b32_e32 v106, v85
	v_mov_b32_e32 v107, v89
	v_mov_b32_e32 v114, v87
	v_mov_b32_e32 v115, v91
	v_mul_f32_e32 v122, v15, v15
	v_mov_b32_e32 v105, v119
	v_mov_b32_e32 v113, v124
	v_mov_b32_e32 v117, v125
	v_pk_add_f32 v[96:97], v[96:97], v[98:99]
	v_mov_b32_e32 v98, v84
	v_mov_b32_e32 v99, v88
	v_mov_b32_e32 v110, v86
	v_mov_b32_e32 v111, v90
	v_pk_mul_f32 v[118:119], v[94:95], v[94:95]
	v_pk_mul_f32 v[120:121], v[92:93], v[92:93]
	v_pk_mul_f32 v[106:107], v[106:107], v[106:107]
	v_pk_mul_f32 v[114:115], v[114:115], v[114:115]
	v_mul_f32_e32 v79, v12, v12
	v_mul_f32_e32 v123, v13, v13
	v_mov_b32_e32 v109, v122
	v_pk_add_f32 v[100:101], v[100:101], v[100:101] op_sel:[0,1] op_sel_hi:[1,0]
	v_pk_add_f32 v[112:113], v[112:113], v[116:117]
	v_pk_mov_b32 v[116:117], v[120:121], v[118:119] op_sel:[1,0]
	v_mov_b32_e32 v121, v119
	v_pk_add_f32 v[96:97], v[96:97], v[96:97] op_sel:[0,1] op_sel_hi:[1,0]
	v_pk_fma_f32 v[98:99], v[98:99], v[98:99], v[106:107]
	v_pk_fma_f32 v[106:107], v[110:111], v[110:111], v[114:115]
	v_pk_add_f32 v[104:105], v[104:105], v[108:109]
	v_mul_f32_e32 v108, v49, v49
	v_mul_f32_e32 v122, v51, v51
	v_mov_b32_e32 v101, v123
	v_pk_add_f32 v[110:111], v[116:117], v[120:121]
	v_mov_b32_e32 v97, v79
	v_pk_add_f32 v[98:99], v[98:99], v[106:107]
	v_mul_f32_e32 v129, v44, v44
	v_mul_f32_e32 v130, v45, v45
	v_mul_f32_e32 v131, v46, v46
	v_mul_f32_e32 v132, v47, v47
	v_pk_fma_f32 v[108:109], v[48:49], v[48:49], v[108:109] op_sel_hi:[1,1,0]
	v_pk_fma_f32 v[118:119], v[50:51], v[50:51], v[122:123] op_sel_hi:[1,1,0]
	v_pk_add_f32 v[96:97], v[96:97], v[100:101]
	v_pk_add_f32 v[100:101], v[110:111], v[110:111] op_sel:[0,1] op_sel_hi:[1,0]
	v_pk_add_f32 v[98:99], v[98:99], v[98:99] op_sel:[0,1] op_sel_hi:[1,0]
	v_pk_mul_f32 v[122:123], v[42:43], v[42:43]
	v_pk_mul_f32 v[124:125], v[40:41], v[40:41]
	v_mov_b32_e32 v109, v131
	v_mov_b32_e32 v119, v132
	v_mov_b32_e32 v101, v130
	v_mov_b32_e32 v99, v129
	v_mul_f32_e32 v126, v1, v1
	v_pk_add_f32 v[102:103], v[102:103], v[102:103] op_sel:[0,1] op_sel_hi:[1,0]
	v_pk_mov_b32 v[114:115], v[124:125], v[122:123] op_sel:[1,0]
	v_mov_b32_e32 v125, v123
	v_pk_add_f32 v[106:107], v[108:109], v[118:119]
	v_pk_add_f32 v[98:99], v[98:99], v[100:101]
	v_mul_f32_e32 v127, v0, v0
	v_mov_b32_e32 v103, v126
	v_mul_f32_e32 v126, v37, v37
	v_mul_f32_e32 v128, v39, v39
	v_pk_add_f32 v[108:109], v[114:115], v[124:125]
	v_pk_add_f32 v[96:97], v[96:97], v[104:105]
	v_pk_add_f32 v[98:99], v[98:99], v[106:107]
	v_mul_f32_e32 v133, v32, v32
	v_mul_f32_e32 v134, v33, v33
	v_mul_f32_e32 v135, v34, v34
	v_mul_f32_e32 v136, v35, v35
	v_pk_fma_f32 v[116:117], v[36:37], v[36:37], v[126:127] op_sel_hi:[1,1,0]
	v_pk_fma_f32 v[120:121], v[38:39], v[38:39], v[128:129] op_sel_hi:[1,1,0]
	v_pk_add_f32 v[104:105], v[108:109], v[108:109] op_sel:[0,1] op_sel_hi:[1,0]
	v_pk_add_f32 v[96:97], v[96:97], v[96:97] op_sel:[0,1] op_sel_hi:[1,0]
	v_pk_add_f32 v[98:99], v[98:99], v[98:99] op_sel:[0,1] op_sel_hi:[1,0]
	v_mov_b32_e32 v117, v135
	v_mov_b32_e32 v121, v136
	v_mov_b32_e32 v105, v134
	v_mov_b32_e32 v97, v127
	v_mov_b32_e32 v99, v133
	v_pk_add_f32 v[108:109], v[116:117], v[120:121]
	v_pk_add_f32 v[96:97], v[96:97], v[102:103]
	v_pk_add_f32 v[98:99], v[98:99], v[104:105]
	v_pk_add_f32 v[96:97], v[96:97], v[112:113]
	v_pk_add_f32 v[98:99], v[98:99], v[108:109]
	v_mov_b32_e32 v101, v96
	v_mov_b32_e32 v100, v98
	v_mov_b32_e32 v96, v99
	v_pk_add_f32 v[96:97], v[100:101], v[96:97]
	ds_bpermute_b32 v99, v71, v97
	ds_bpermute_b32 v98, v71, v96
	s_waitcnt lgkmcnt(0)
	v_pk_add_f32 v[96:97], v[96:97], v[98:99]
	ds_bpermute_b32 v99, v74, v97
	ds_bpermute_b32 v98, v74, v96
	s_waitcnt lgkmcnt(0)
	v_pk_add_f32 v[96:97], v[96:97], v[98:99]
	ds_bpermute_b32 v99, v75, v97
	ds_bpermute_b32 v98, v75, v96
	s_waitcnt lgkmcnt(0)
	v_pk_add_f32 v[96:97], v[96:97], v[98:99]
	ds_bpermute_b32 v99, v76, v97
	ds_bpermute_b32 v98, v76, v96
	s_waitcnt lgkmcnt(0)
	v_pk_add_f32 v[96:97], v[96:97], v[98:99]
	ds_bpermute_b32 v99, v77, v97
	ds_bpermute_b32 v98, v77, v96
	s_waitcnt lgkmcnt(0)
	v_pk_add_f32 v[96:97], v[96:97], v[98:99]
	ds_bpermute_b32 v99, v78, v97
	ds_bpermute_b32 v98, v78, v96
	s_waitcnt lgkmcnt(0)
; __device__ __forceinline__ unsigned cvt_pk_bf16(float lo, float hi) { f32x2_c v = {lo, hi}; bf16x2_c r = __builtin_convertvector(v, bf16x2_c); return __builtin_bit_cast(unsigned, r); }
; __device__ __forceinline__ void rms_row2_bf16(const float* xa, const float* xb, const float* g, bf16_t* oa, bf16_t* ob, int lane) {
;     ...
;     const float ra = rsqrtf(wave_sum(sa) * (1.f / D) + EPS), rb = rsqrtf(wave_sum(sb) * (1.f / D) + EPS);
; #pragma unroll
;     for (int j = 0; j < 8; ++j) { const f32x4 gg = ((const f32x4*)g)[lane + 64 * j]; u32x2 o;
;         o.x = cvt_pk_bf16(va[j][0] * ra * gg[0], va[j][1] * ra * gg[1]); o.y = cvt_pk_bf16(va[j][2] * ra * gg[2], va[j][3] * ra * gg[3]); __builtin_nontemporal_store(o, (u32x2*)oa + lane + 64 * j);
;         o.x = cvt_pk_bf16(vb[j][0] * rb * gg[0], vb[j][1] * rb * gg[1]); o.y = cvt_pk_bf16(vb[j][2] * rb * gg[2], vb[j][3] * rb * gg[3]); __builtin_nontemporal_store(o, (u32x2*)ob + lane + 64 * j); }
; __global__ void __launch_bounds__(NTHREADS, 2) fwd_kernel(Args args) {
;     ...
;         norm_all_bf16(out, xattn_norm, XN, gw, NGW, lane);
	v_pk_add_f32 v[96:97], v[96:97], v[98:99]
	s_nop 0
	v_pk_fma_f32 v[96:97], v[96:97], s[12:13], v[70:71] op_sel_hi:[1,0,0]
	s_nop 0
	v_mul_f32_e32 v79, 0x4b800000, v97
	v_cmp_gt_f32_e64 s[0:1], s16, v97
	v_mul_f32_e32 v98, 0x4b800000, v96
	v_cmp_gt_f32_e32 vcc, s16, v96
	v_cndmask_b32_e64 v79, v97, v79, s[0:1]
	v_rsq_f32_e32 v79, v79
	v_cndmask_b32_e32 v96, v96, v98, vcc
	v_rsq_f32_e32 v97, v96
	v_mul_f32_e32 v96, 0x45800000, v79
	v_cndmask_b32_e64 v96, v79, v96, s[0:1]
	v_mul_f32_e32 v98, 0x45800000, v97
	v_cndmask_b32_e32 v98, v97, v98, vcc
	v_pk_mul_f32 v[28:29], v[28:29], v[96:97] op_sel_hi:[1,0]
	v_pk_mul_f32 v[30:31], v[30:31], v[96:97] op_sel_hi:[1,0]
	v_pk_mul_f32 v[84:85], v[84:85], v[98:99] op_sel_hi:[1,0]
	v_pk_mul_f32 v[86:87], v[86:87], v[98:99] op_sel_hi:[1,0]
	v_pk_mul_f32 v[28:29], v[138:139], v[28:29]
	v_pk_mul_f32 v[30:31], v[140:141], v[30:31]
	v_pk_mul_f32 v[80:81], v[138:139], v[84:85]
	v_pk_mul_f32 v[82:83], v[140:141], v[86:87]
	v_cvt_pk_bf16_f32 v28, v28, v29
	v_cvt_pk_bf16_f32 v29, v30, v31
	v_cvt_pk_bf16_f32 v30, v80, v81
	v_cvt_pk_bf16_f32 v31, v82, v83
	global_store_dwordx2 v[68:69], v[28:29], off nt
	global_store_dwordx2 v[72:73], v[30:31], off nt
	v_pk_mul_f32 v[24:25], v[24:25], v[96:97] op_sel_hi:[1,0]
	v_pk_mul_f32 v[26:27], v[26:27], v[96:97] op_sel_hi:[1,0]
	v_pk_mul_f32 v[80:81], v[88:89], v[98:99] op_sel_hi:[1,0]
	v_pk_mul_f32 v[82:83], v[90:91], v[98:99] op_sel_hi:[1,0]
	v_pk_mul_f32 v[20:21], v[20:21], v[96:97] op_sel_hi:[1,0]
	v_pk_mul_f32 v[22:23], v[22:23], v[96:97] op_sel_hi:[1,0]
	v_pk_mul_f32 v[16:17], v[16:17], v[96:97] op_sel_hi:[1,0]
	v_pk_mul_f32 v[18:19], v[18:19], v[96:97] op_sel_hi:[1,0]
	v_pk_mul_f32 v[12:13], v[12:13], v[96:97] op_sel_hi:[1,0]
	v_pk_mul_f32 v[14:15], v[14:15], v[96:97] op_sel_hi:[1,0]
	v_pk_mul_f32 v[8:9], v[8:9], v[96:97] op_sel_hi:[1,0]
	v_pk_mul_f32 v[10:11], v[10:11], v[96:97] op_sel_hi:[1,0]
	v_pk_mul_f32 v[4:5], v[4:5], v[96:97] op_sel_hi:[1,0]
	v_pk_mul_f32 v[6:7], v[6:7], v[96:97] op_sel_hi:[1,0]
	v_pk_mul_f32 v[0:1], v[0:1], v[96:97] op_sel_hi:[1,0]
	v_pk_mul_f32 v[2:3], v[2:3], v[96:97] op_sel_hi:[1,0]
	s_add_i32 s0, s13, s17
	s_cmpk_gt_i32 s0, 0x7fff
	v_pk_mul_f32 v[24:25], v[142:143], v[24:25]
	v_pk_mul_f32 v[26:27], v[144:145], v[26:27]
	v_pk_mul_f32 v[28:29], v[142:143], v[80:81]
	v_pk_mul_f32 v[30:31], v[144:145], v[82:83]
	v_cvt_pk_bf16_f32 v24, v24, v25
	v_cvt_pk_bf16_f32 v25, v26, v27
	v_cvt_pk_bf16_f32 v26, v28, v29
	v_cvt_pk_bf16_f32 v27, v30, v31
	global_store_dwordx2 v[68:69], v[24:25], off offset:512 nt
	global_store_dwordx2 v[72:73], v[26:27], off offset:512 nt
	v_pk_mul_f32 v[28:29], v[92:93], v[98:99] op_sel_hi:[1,0]
	v_pk_mul_f32 v[30:31], v[94:95], v[98:99] op_sel_hi:[1,0]
	v_pk_mul_f32 v[20:21], v[20:21], v[146:147]
	v_pk_mul_f32 v[22:23], v[22:23], v[148:149]
	v_pk_mul_f32 v[24:25], v[146:147], v[28:29]
	v_pk_mul_f32 v[26:27], v[148:149], v[30:31]
	v_cvt_pk_bf16_f32 v20, v20, v21
	v_cvt_pk_bf16_f32 v21, v22, v23
	v_cvt_pk_bf16_f32 v22, v24, v25
	v_cvt_pk_bf16_f32 v23, v26, v27
	global_store_dwordx2 v[68:69], v[20:21], off offset:1024 nt
	global_store_dwordx2 v[72:73], v[22:23], off offset:1024 nt
	v_pk_mul_f32 v[24:25], v[48:49], v[98:99] op_sel_hi:[1,0]
	v_pk_mul_f32 v[26:27], v[50:51], v[98:99] op_sel_hi:[1,0]
	v_pk_mul_f32 v[16:17], v[16:17], v[150:151]
	v_pk_mul_f32 v[18:19], v[18:19], v[152:153]
	v_pk_mul_f32 v[20:21], v[24:25], v[150:151]
	v_pk_mul_f32 v[22:23], v[26:27], v[152:153]
	v_cvt_pk_bf16_f32 v16, v16, v17
	v_cvt_pk_bf16_f32 v17, v18, v19
	v_cvt_pk_bf16_f32 v18, v20, v21
	v_cvt_pk_bf16_f32 v19, v22, v23
	global_store_dwordx2 v[68:69], v[16:17], off offset:1536 nt
	global_store_dwordx2 v[72:73], v[18:19], off offset:1536 nt
	v_pk_mul_f32 v[20:21], v[44:45], v[98:99] op_sel_hi:[1,0]
	v_pk_mul_f32 v[22:23], v[46:47], v[98:99] op_sel_hi:[1,0]
	v_pk_mul_f32 v[12:13], v[12:13], v[154:155]
	v_pk_mul_f32 v[14:15], v[14:15], v[156:157]
	v_pk_mul_f32 v[16:17], v[20:21], v[154:155]
	v_pk_mul_f32 v[18:19], v[22:23], v[156:157]
	v_cvt_pk_bf16_f32 v12, v12, v13
	v_cvt_pk_bf16_f32 v13, v14, v15
	v_cvt_pk_bf16_f32 v14, v16, v17
	v_cvt_pk_bf16_f32 v15, v18, v19
	global_store_dwordx2 v[68:69], v[12:13], off offset:2048 nt
	global_store_dwordx2 v[72:73], v[14:15], off offset:2048 nt
	v_pk_mul_f32 v[16:17], v[40:41], v[98:99] op_sel_hi:[1,0]
	v_pk_mul_f32 v[18:19], v[42:43], v[98:99] op_sel_hi:[1,0]
	v_pk_mul_f32 v[8:9], v[8:9], v[158:159]
	v_pk_mul_f32 v[10:11], v[10:11], v[160:161]
	v_pk_mul_f32 v[12:13], v[16:17], v[158:159]
	v_pk_mul_f32 v[14:15], v[18:19], v[160:161]
	v_cvt_pk_bf16_f32 v8, v8, v9
	v_cvt_pk_bf16_f32 v9, v10, v11
	v_cvt_pk_bf16_f32 v10, v12, v13
	v_cvt_pk_bf16_f32 v11, v14, v15
	global_store_dwordx2 v[68:69], v[8:9], off offset:2560 nt
	global_store_dwordx2 v[72:73], v[10:11], off offset:2560 nt
	v_pk_mul_f32 v[12:13], v[36:37], v[98:99] op_sel_hi:[1,0]
	v_pk_mul_f32 v[14:15], v[38:39], v[98:99] op_sel_hi:[1,0]
	v_pk_mul_f32 v[4:5], v[4:5], v[162:163]
	v_pk_mul_f32 v[6:7], v[6:7], v[164:165]
	v_pk_mul_f32 v[8:9], v[12:13], v[162:163]
	v_pk_mul_f32 v[10:11], v[14:15], v[164:165]
	v_cvt_pk_bf16_f32 v4, v4, v5
	v_cvt_pk_bf16_f32 v5, v6, v7
	v_cvt_pk_bf16_f32 v6, v8, v9
	v_cvt_pk_bf16_f32 v7, v10, v11
	global_store_dwordx2 v[68:69], v[4:5], off offset:3072 nt
	global_store_dwordx2 v[72:73], v[6:7], off offset:3072 nt
	v_pk_mul_f32 v[8:9], v[32:33], v[98:99] op_sel_hi:[1,0]
	v_pk_mul_f32 v[10:11], v[34:35], v[98:99] op_sel_hi:[1,0]
	v_pk_mul_f32 v[0:1], v[0:1], v[168:169]
	v_pk_mul_f32 v[2:3], v[2:3], v[170:171]
	v_pk_mul_f32 v[4:5], v[8:9], v[168:169]
	v_pk_mul_f32 v[6:7], v[10:11], v[170:171]
	v_cvt_pk_bf16_f32 v0, v0, v1
	v_cvt_pk_bf16_f32 v1, v2, v3
	v_cvt_pk_bf16_f32 v2, v4, v5
	v_cvt_pk_bf16_f32 v3, v6, v7
	global_store_dwordx2 v[68:69], v[0:1], off offset:3584 nt
	global_store_dwordx2 v[72:73], v[2:3], off offset:3584 nt
	v_lshl_add_u64 v[68:69], v[68:69], 0, s[10:11]
	s_cbranch_scc0 .LBB0_1057
	v_readlane_b32 s0, v245, 40
	s_add_i32 s0, s0, s17

; __device__ __forceinline__ void rms_row2_bf16(const float* xa, const float* xb, const float* g, bf16_t* oa, bf16_t* ob, int lane) {
;     f32x4 va[8], vb[8]; float sa = 0.f, sb = 0.f;
; #pragma unroll
;     for (int j = 0; j < 8; ++j) { va[j] = __builtin_nontemporal_load((const f32x4*)xa + lane + 64 * j); vb[j] = __builtin_nontemporal_load((const f32x4*)xb + lane + 64 * j); }
; #pragma unroll
; __device__ __forceinline__ void norm_all_bf16(const float* src, const float* g, bf16_t* dst, int gw, int NGW, int lane) {
;     int m = gw;
;     for (; m + NGW < T; m += 2 * NGW) rms_row2_bf16(src + (size_t)m * D, src + (size_t)(m + NGW) * D, g, dst + (size_t)m * D, dst + (size_t)(m + NGW) * D, lane);
.LBB0_1297:
	s_cmp_lt_i32 s90, 15
	s_cselect_b64 s[2:3], -1, 0
	s_and_b64 s[0:1], s[2:3], s[4:5]
	s_andn2_b64 vcc, exec, s[0:1]
	s_cbranch_vccnz .LBB0_1305
	v_readlane_b32 s0, v244, 9
	s_add_i32 s12, s0, s36
	s_cmpk_gt_i32 s12, 0x7fff
	v_lshlrev_b32_e32 v52, 3, v176
	v_readlane_b32 s1, v244, 10
	s_cbranch_scc1 .LBB0_1302
	v_mbcnt_lo_u32_b32 v2, -1, 0
	v_mbcnt_hi_u32_b32 v2, -1, v2
	v_and_b32_e32 v3, 64, v2
	v_add_u32_e32 v3, 64, v3
	v_xor_b32_e32 v4, 1, v2
	v_cmp_lt_i32_e32 vcc, v4, v3
	v_readlane_b32 s4, v244, 1
	v_lshlrev_b32_e32 v0, 4, v176
	v_cndmask_b32_e32 v4, v2, v4, vcc
	v_mov_b32_e32 v1, 0
	v_lshlrev_b32_e32 v73, 2, v4
	v_xor_b32_e32 v4, 2, v2
	v_readlane_b32 s5, v244, 2
	v_readlane_b32 s6, v244, 3
	v_readlane_b32 s7, v244, 4
	v_cmp_lt_i32_e32 vcc, v4, v3
	s_mov_b64 s[4:5], 0x1400
	v_lshl_add_u64 v[58:59], s[6:7], 0, v[0:1]
	v_cndmask_b32_e32 v4, v2, v4, vcc
	v_lshl_add_u64 v[62:63], v[58:59], 0, s[4:5]
	s_mov_b64 s[4:5], 0x1800
	v_readlane_b32 s6, v245, 1
	v_lshlrev_b32_e32 v76, 2, v4
	v_xor_b32_e32 v4, 4, v2
	v_lshl_add_u64 v[64:65], v[58:59], 0, s[4:5]
	s_mov_b64 s[4:5], 0x1c00
	v_readlane_b32 s7, v245, 2
	v_cmp_lt_i32_e32 vcc, v4, v3
	v_lshl_add_u64 v[66:67], v[58:59], 0, s[4:5]
	s_lshl_b32 s4, s6, 4
	s_add_i32 s5, s83, s6
	v_readlane_b32 s6, v244, 9
	v_cndmask_b32_e32 v4, v2, v4, vcc
	v_readlane_b32 s11, v244, 8
	v_readlane_b32 s7, v244, 10
	s_mov_b32 s16, s6
	s_ashr_i32 s17, s6, 31
	v_lshlrev_b32_e32 v77, 2, v4
	v_xor_b32_e32 v4, 8, v2
	s_lshl_b32 s11, s5, 3
	s_lshl_b64 s[6:7], s[16:17], 13
	v_cmp_lt_i32_e32 vcc, v4, v3
	s_add_u32 s6, s86, s6
	s_addc_u32 s7, s87, s7
	v_cndmask_b32_e32 v4, v2, v4, vcc
	v_lshl_add_u64 v[54:55], s[86:87], 0, v[0:1]
	v_lshlrev_b32_e32 v78, 2, v4
	v_xor_b32_e32 v4, 16, v2
	v_mov_b32_e32 v53, v1
	s_mov_b64 s[0:1], 0x1000
	v_lshl_add_u64 v[0:1], s[6:7], 0, v[0:1]
	s_ashr_i32 s5, s4, 31
	v_cmp_lt_i32_e32 vcc, v4, v3
	v_lshl_add_u64 v[60:61], v[58:59], 0, s[0:1]
	v_lshl_add_u64 v[68:69], v[0:1], 0, s[0:1]
	s_lshl_b64 s[6:7], s[4:5], 13
	s_lshl_b64 s[0:1], s[16:17], 12
	v_cndmask_b32_e32 v4, v2, v4, vcc
	s_add_u32 s0, s88, s0
	v_lshlrev_b32_e32 v79, 2, v4
	v_xor_b32_e32 v4, 32, v2
	s_addc_u32 s1, s89, s1
	v_cmp_lt_i32_e32 vcc, v4, v3
	v_lshl_add_u64 v[0:1], s[0:1], 0, v[52:53]
	s_mov_b64 s[0:1], 0xde00000
	v_cndmask_b32_e32 v2, v2, v4, vcc
	v_readlane_b32 s8, v244, 5
	v_readlane_b32 s9, v244, 6
	v_readlane_b32 s10, v244, 7
	v_lshl_add_u64 v[70:71], v[0:1], 0, s[0:1]
	s_mov_b32 s0, s16
	v_lshlrev_b32_e32 v80, 2, v2
	v_lshl_add_u64 v[56:57], s[80:81], 0, v[52:53]
	s_lshl_b64 s[8:9], s[4:5], 12
	s_movk_i32 s5, 0x1000
	s_mov_b32 s10, 0x3a000000
	v_mov_b32_e32 v72, 0x358637bd
	s_mov_b32 s14, 0x800000
	v_writelane_b32 v244, s0, 9
	s_mov_b32 s15, s16
	s_nop 0
	v_writelane_b32 v244, s1, 10
	global_load_dwordx4 v[138:141], v[58:59], off
	global_load_dwordx4 v[142:145], v[58:59], off offset:1024
	global_load_dwordx4 v[146:149], v[58:59], off offset:2048
	global_load_dwordx4 v[150:153], v[58:59], off offset:3072
	global_load_dwordx4 v[154:157], v[60:61], off
	global_load_dwordx4 v[158:161], v[62:63], off
	global_load_dwordx4 v[162:165], v[64:65], off
	global_load_dwordx4 v[168:171], v[66:67], off
.LBB0_1300:
	global_load_dwordx4 v[28:31], v[68:69], off offset:-4096 nt
	global_load_dwordx4 v[24:27], v[68:69], off offset:-3072 nt
	global_load_dwordx4 v[20:23], v[68:69], off offset:-2048 nt
	global_load_dwordx4 v[12:15], v[68:69], off nt
	global_load_dwordx4 v[16:19], v[68:69], off offset:-1024 nt
	global_load_dwordx4 v[8:11], v[68:69], off offset:1024 nt
	global_load_dwordx4 v[0:3], v[68:69], off offset:3072 nt
	global_load_dwordx4 v[4:7], v[68:69], off offset:2048 nt
	s_ashr_i32 s13, s12, 31
	s_lshl_b64 s[0:1], s[12:13], 13
	v_lshl_add_u64 v[32:33], v[54:55], 0, s[0:1]
	global_load_dwordx4 v[86:89], v[32:33], off nt
	global_load_dwordx4 v[90:93], v[32:33], off offset:1024 nt
	global_load_dwordx4 v[94:97], v[32:33], off offset:2048 nt
	global_load_dwordx4 v[48:51], v[32:33], off offset:3072 nt
	v_add_co_u32_e32 v98, vcc, s5, v32
	s_lshl_b64 s[12:13], s[12:13], 12
	s_nop 0
	v_addc_co_u32_e32 v99, vcc, 0, v33, vcc
	global_load_dwordx4 v[44:47], v[98:99], off nt
	global_load_dwordx4 v[40:43], v[98:99], off offset:1024 nt
	global_load_dwordx4 v[32:35], v[98:99], off offset:3072 nt
	global_load_dwordx4 v[36:39], v[98:99], off offset:2048 nt
	v_lshl_add_u64 v[74:75], v[56:57], 0, s[12:13]
	s_add_i32 s15, s15, s4
	s_add_i32 s82, s82, s4
	s_add_i32 s12, s15, s36
	v_lshl_add_u64 v[68:69], v[68:69], 0, s[6:7]
	s_waitcnt vmcnt(0)
; __device__ __forceinline__ float wave_sum(float v) {
; #pragma unroll
;     for (int o = 1; o < 64; o <<= 1) v += __shfl_xor(v, o);
;     return v;
; __device__ __forceinline__ void rms_row2_bf16(const float* xa, const float* xb, const float* g, bf16_t* oa, bf16_t* ob, int lane) {
;     ...
; #pragma unroll
;     for (int j = 0; j < 8; ++j) { sa += (va[j][0] * va[j][0] + va[j][1] * va[j][1]) + (va[j][2] * va[j][2] + va[j][3] * va[j][3]); sb += (vb[j][0] * vb[j][0] + vb[j][1] * vb[j][1]) + (vb[j][2] * vb[j][2] + vb[j][3] * vb[j][3]); }
;     const float ra = rsqrtf(wave_sum(sa) * (1.f / D) + EPS), rb = rsqrtf(wave_sum(sb) * (1.f / D) + EPS);
	v_mov_b32_e32 v100, v29
	v_mov_b32_e32 v101, v25
	v_mov_b32_e32 v104, v31
	v_mov_b32_e32 v105, v27
	v_pk_mul_f32 v[106:107], v[22:23], v[22:23]
	v_pk_mul_f32 v[108:109], v[20:21], v[20:21]
	v_mul_f32_e32 v110, v17, v17
	v_mul_f32_e32 v112, v19, v19
	v_pk_mul_f32 v[114:115], v[10:11], v[10:11]
	v_pk_mul_f32 v[116:117], v[8:9], v[8:9]
	v_mov_b32_e32 v98, v28
	v_mov_b32_e32 v99, v24
	v_mov_b32_e32 v102, v30
	v_mov_b32_e32 v103, v26
	v_mul_f32_e32 v121, v14, v14
	v_mul_f32_e32 v118, v5, v5
	v_mul_f32_e32 v120, v7, v7
	v_pk_mul_f32 v[100:101], v[100:101], v[100:101]
	v_pk_mul_f32 v[104:105], v[104:105], v[104:105]
	v_pk_mov_b32 v[122:123], v[108:109], v[106:107] op_sel:[1,0]
	v_mov_b32_e32 v109, v107
	v_pk_fma_f32 v[106:107], v[16:17], v[16:17], v[110:111] op_sel_hi:[1,1,0]
	v_pk_fma_f32 v[110:111], v[18:19], v[18:19], v[112:113] op_sel_hi:[1,1,0]
	v_pk_mov_b32 v[112:113], v[116:117], v[114:115] op_sel:[1,0]
	v_mov_b32_e32 v117, v115
	v_mul_f32_e32 v125, v2, v2
	v_mul_f32_e32 v126, v3, v3
	v_pk_fma_f32 v[114:115], v[4:5], v[4:5], v[118:119] op_sel_hi:[1,1,0]
	v_pk_fma_f32 v[118:119], v[6:7], v[6:7], v[120:121] op_sel_hi:[1,1,0]
	v_pk_fma_f32 v[98:99], v[98:99], v[98:99], v[100:101]
	v_pk_fma_f32 v[100:101], v[102:103], v[102:103], v[104:105]
	v_pk_add_f32 v[102:103], v[122:123], v[108:109]
	v_pk_add_f32 v[104:105], v[112:113], v[116:117]
	v_mov_b32_e32 v108, v87
	v_mov_b32_e32 v109, v91
	v_mov_b32_e32 v116, v89
	v_mov_b32_e32 v117, v93
	v_mul_f32_e32 v124, v15, v15
	v_mov_b32_e32 v107, v121
	v_mov_b32_e32 v115, v125
	v_mov_b32_e32 v119, v126
	v_pk_add_f32 v[98:99], v[98:99], v[100:101]
	v_mov_b32_e32 v100, v86
	v_mov_b32_e32 v101, v90
	v_mov_b32_e32 v112, v88
	v_mov_b32_e32 v113, v92
	v_pk_mul_f32 v[120:121], v[96:97], v[96:97]
	v_pk_mul_f32 v[122:123], v[94:95], v[94:95]
	v_pk_mul_f32 v[108:109], v[108:109], v[108:109]
	v_pk_mul_f32 v[116:117], v[116:117], v[116:117]
	v_mul_f32_e32 v53, v12, v12
	v_mul_f32_e32 v81, v13, v13
	v_mov_b32_e32 v111, v124
	v_pk_add_f32 v[102:103], v[102:103], v[102:103] op_sel:[0,1] op_sel_hi:[1,0]
	v_pk_add_f32 v[114:115], v[114:115], v[118:119]
	v_pk_mov_b32 v[118:119], v[122:123], v[120:121] op_sel:[1,0]
	v_mov_b32_e32 v123, v121
	v_pk_add_f32 v[98:99], v[98:99], v[98:99] op_sel:[0,1] op_sel_hi:[1,0]
	v_pk_fma_f32 v[100:101], v[100:101], v[100:101], v[108:109]
	v_pk_fma_f32 v[108:109], v[112:113], v[112:113], v[116:117]
	v_pk_add_f32 v[106:107], v[106:107], v[110:111]
	v_mul_f32_e32 v110, v49, v49
	v_mul_f32_e32 v124, v51, v51
	v_mov_b32_e32 v103, v81
	v_pk_add_f32 v[112:113], v[118:119], v[122:123]
	v_mov_b32_e32 v99, v53
	v_pk_add_f32 v[100:101], v[100:101], v[108:109]
	v_mul_f32_e32 v81, v44, v44
	v_mul_f32_e32 v131, v45, v45
	v_mul_f32_e32 v132, v46, v46
	v_mul_f32_e32 v133, v47, v47
	v_pk_fma_f32 v[110:111], v[48:49], v[48:49], v[110:111] op_sel_hi:[1,1,0]
	v_pk_fma_f32 v[120:121], v[50:51], v[50:51], v[124:125] op_sel_hi:[1,1,0]
	v_pk_add_f32 v[98:99], v[98:99], v[102:103]
	v_pk_add_f32 v[102:103], v[112:113], v[112:113] op_sel:[0,1] op_sel_hi:[1,0]
	v_pk_add_f32 v[100:101], v[100:101], v[100:101] op_sel:[0,1] op_sel_hi:[1,0]
	v_pk_mul_f32 v[124:125], v[42:43], v[42:43]
	v_pk_mul_f32 v[126:127], v[40:41], v[40:41]
	v_mov_b32_e32 v111, v132
	v_mov_b32_e32 v121, v133
	v_mov_b32_e32 v103, v131
	v_mov_b32_e32 v101, v81
	v_mul_f32_e32 v128, v1, v1
	v_pk_add_f32 v[104:105], v[104:105], v[104:105] op_sel:[0,1] op_sel_hi:[1,0]
	v_pk_mov_b32 v[116:117], v[126:127], v[124:125] op_sel:[1,0]
	v_mov_b32_e32 v127, v125
	v_pk_add_f32 v[108:109], v[110:111], v[120:121]
	v_pk_add_f32 v[100:101], v[100:101], v[102:103]
	v_mul_f32_e32 v129, v0, v0
	v_mov_b32_e32 v105, v128
	v_mul_f32_e32 v128, v37, v37
	v_mul_f32_e32 v130, v39, v39
	v_pk_add_f32 v[110:111], v[116:117], v[126:127]
	v_pk_add_f32 v[98:99], v[98:99], v[106:107]
	v_pk_add_f32 v[100:101], v[100:101], v[108:109]
	v_mul_f32_e32 v134, v32, v32
	v_mul_f32_e32 v135, v33, v33
	v_mul_f32_e32 v136, v34, v34
	v_mul_f32_e32 v137, v35, v35
	v_pk_fma_f32 v[118:119], v[36:37], v[36:37], v[128:129] op_sel_hi:[1,1,0]
	v_pk_fma_f32 v[122:123], v[38:39], v[38:39], v[130:131] op_sel_hi:[1,1,0]
	v_pk_add_f32 v[106:107], v[110:111], v[110:111] op_sel:[0,1] op_sel_hi:[1,0]
	v_pk_add_f32 v[98:99], v[98:99], v[98:99] op_sel:[0,1] op_sel_hi:[1,0]
	v_pk_add_f32 v[100:101], v[100:101], v[100:101] op_sel:[0,1] op_sel_hi:[1,0]
	v_mov_b32_e32 v119, v136
	v_mov_b32_e32 v123, v137
	v_mov_b32_e32 v107, v135
	v_mov_b32_e32 v99, v129
	v_mov_b32_e32 v101, v134
	v_pk_add_f32 v[110:111], v[118:119], v[122:123]
	v_pk_add_f32 v[98:99], v[98:99], v[104:105]
	v_pk_add_f32 v[100:101], v[100:101], v[106:107]
	v_pk_add_f32 v[98:99], v[98:99], v[114:115]
	v_pk_add_f32 v[100:101], v[100:101], v[110:111]
	v_mov_b32_e32 v103, v98
	v_mov_b32_e32 v102, v100
	v_mov_b32_e32 v98, v101
	v_pk_add_f32 v[98:99], v[102:103], v[98:99]
	ds_bpermute_b32 v101, v73, v99
	ds_bpermute_b32 v100, v73, v98
	s_waitcnt lgkmcnt(0)
	v_pk_add_f32 v[98:99], v[98:99], v[100:101]
	ds_bpermute_b32 v101, v76, v99
	ds_bpermute_b32 v100, v76, v98
	s_waitcnt lgkmcnt(0)
	v_pk_add_f32 v[98:99], v[98:99], v[100:101]
	ds_bpermute_b32 v101, v77, v99
	ds_bpermute_b32 v100, v77, v98
	s_waitcnt lgkmcnt(0)
	v_pk_add_f32 v[98:99], v[98:99], v[100:101]
	ds_bpermute_b32 v101, v78, v99
	ds_bpermute_b32 v100, v78, v98
	s_waitcnt lgkmcnt(0)
	v_pk_add_f32 v[98:99], v[98:99], v[100:101]
	ds_bpermute_b32 v101, v79, v99
	ds_bpermute_b32 v100, v79, v98
	s_waitcnt lgkmcnt(0)
	v_pk_add_f32 v[98:99], v[98:99], v[100:101]
	ds_bpermute_b32 v101, v80, v99
	ds_bpermute_b32 v100, v80, v98
	s_waitcnt lgkmcnt(0)
; __device__ __forceinline__ unsigned cvt_pk_bf16(float lo, float hi) { f32x2_c v = {lo, hi}; bf16x2_c r = __builtin_convertvector(v, bf16x2_c); return __builtin_bit_cast(unsigned, r); }
; __device__ __forceinline__ void rms_row2_bf16(const float* xa, const float* xb, const float* g, bf16_t* oa, bf16_t* ob, int lane) {
;     ...
;     const float ra = rsqrtf(wave_sum(sa) * (1.f / D) + EPS), rb = rsqrtf(wave_sum(sb) * (1.f / D) + EPS);
; #pragma unroll
;     for (int j = 0; j < 8; ++j) { const f32x4 gg = ((const f32x4*)g)[lane + 64 * j]; u32x2 o;
;         o.x = cvt_pk_bf16(va[j][0] * ra * gg[0], va[j][1] * ra * gg[1]); o.y = cvt_pk_bf16(va[j][2] * ra * gg[2], va[j][3] * ra * gg[3]); __builtin_nontemporal_store(o, (u32x2*)oa + lane + 64 * j);
;         o.x = cvt_pk_bf16(vb[j][0] * rb * gg[0], vb[j][1] * rb * gg[1]); o.y = cvt_pk_bf16(vb[j][2] * rb * gg[2], vb[j][3] * rb * gg[3]); __builtin_nontemporal_store(o, (u32x2*)ob + lane + 64 * j); }
	v_pk_add_f32 v[98:99], v[98:99], v[100:101]
	s_nop 0
	v_pk_fma_f32 v[98:99], v[98:99], s[10:11], v[72:73] op_sel_hi:[1,0,0]
	s_nop 0
	v_mul_f32_e32 v53, 0x4b800000, v99
	v_cmp_gt_f32_e64 s[0:1], s14, v99
	v_mul_f32_e32 v81, 0x4b800000, v98
	v_cmp_gt_f32_e32 vcc, s14, v98
	v_cndmask_b32_e64 v53, v99, v53, s[0:1]
	v_rsq_f32_e32 v53, v53
	v_cndmask_b32_e32 v81, v98, v81, vcc
	v_rsq_f32_e32 v81, v81
	v_mul_f32_e32 v98, 0x45800000, v53
	v_cndmask_b32_e64 v98, v53, v98, s[0:1]
	v_mul_f32_e32 v99, 0x45800000, v81
	v_cndmask_b32_e32 v100, v81, v99, vcc
	v_pk_mul_f32 v[28:29], v[28:29], v[98:99] op_sel_hi:[1,0]
	v_pk_mul_f32 v[30:31], v[30:31], v[98:99] op_sel_hi:[1,0]
	v_pk_mul_f32 v[86:87], v[86:87], v[100:101] op_sel_hi:[1,0]
	v_pk_mul_f32 v[88:89], v[88:89], v[100:101] op_sel_hi:[1,0]
	v_pk_mul_f32 v[28:29], v[138:139], v[28:29]
	v_pk_mul_f32 v[30:31], v[140:141], v[30:31]
	v_pk_mul_f32 v[82:83], v[138:139], v[86:87]
	v_pk_mul_f32 v[84:85], v[140:141], v[88:89]
	v_cvt_pk_bf16_f32 v28, v28, v29
	v_cvt_pk_bf16_f32 v29, v30, v31
	v_cvt_pk_bf16_f32 v30, v82, v83
	v_cvt_pk_bf16_f32 v31, v84, v85
	global_store_dwordx2 v[70:71], v[28:29], off nt
	global_store_dwordx2 v[74:75], v[30:31], off nt
	v_pk_mul_f32 v[24:25], v[24:25], v[98:99] op_sel_hi:[1,0]
	v_pk_mul_f32 v[26:27], v[26:27], v[98:99] op_sel_hi:[1,0]
	v_pk_mul_f32 v[82:83], v[90:91], v[100:101] op_sel_hi:[1,0]
	v_pk_mul_f32 v[84:85], v[92:93], v[100:101] op_sel_hi:[1,0]
	v_pk_mul_f32 v[20:21], v[20:21], v[98:99] op_sel_hi:[1,0]
	v_pk_mul_f32 v[22:23], v[22:23], v[98:99] op_sel_hi:[1,0]
	v_pk_mul_f32 v[16:17], v[16:17], v[98:99] op_sel_hi:[1,0]
	v_pk_mul_f32 v[18:19], v[18:19], v[98:99] op_sel_hi:[1,0]
	v_pk_mul_f32 v[12:13], v[12:13], v[98:99] op_sel_hi:[1,0]
	v_pk_mul_f32 v[14:15], v[14:15], v[98:99] op_sel_hi:[1,0]
	v_pk_mul_f32 v[8:9], v[8:9], v[98:99] op_sel_hi:[1,0]
	v_pk_mul_f32 v[10:11], v[10:11], v[98:99] op_sel_hi:[1,0]
	v_pk_mul_f32 v[4:5], v[4:5], v[98:99] op_sel_hi:[1,0]
	v_pk_mul_f32 v[6:7], v[6:7], v[98:99] op_sel_hi:[1,0]
	v_pk_mul_f32 v[0:1], v[0:1], v[98:99] op_sel_hi:[1,0]
	v_pk_mul_f32 v[2:3], v[2:3], v[98:99] op_sel_hi:[1,0]
	s_add_i32 s0, s11, s82
	s_cmpk_gt_i32 s0, 0x7fff
	v_pk_mul_f32 v[24:25], v[142:143], v[24:25]
	v_pk_mul_f32 v[26:27], v[144:145], v[26:27]
	v_pk_mul_f32 v[28:29], v[142:143], v[82:83]
	v_pk_mul_f32 v[30:31], v[144:145], v[84:85]
	v_cvt_pk_bf16_f32 v24, v24, v25
	v_cvt_pk_bf16_f32 v25, v26, v27
	v_cvt_pk_bf16_f32 v26, v28, v29
	v_cvt_pk_bf16_f32 v27, v30, v31
	global_store_dwordx2 v[70:71], v[24:25], off offset:512 nt
	global_store_dwordx2 v[74:75], v[26:27], off offset:512 nt
	v_pk_mul_f32 v[28:29], v[94:95], v[100:101] op_sel_hi:[1,0]
	v_pk_mul_f32 v[30:31], v[96:97], v[100:101] op_sel_hi:[1,0]
	v_pk_mul_f32 v[20:21], v[20:21], v[146:147]
	v_pk_mul_f32 v[22:23], v[22:23], v[148:149]
	v_pk_mul_f32 v[24:25], v[146:147], v[28:29]
	v_pk_mul_f32 v[26:27], v[148:149], v[30:31]
	v_cvt_pk_bf16_f32 v20, v20, v21
	v_cvt_pk_bf16_f32 v21, v22, v23
	v_cvt_pk_bf16_f32 v22, v24, v25
	v_cvt_pk_bf16_f32 v23, v26, v27
	global_store_dwordx2 v[70:71], v[20:21], off offset:1024 nt
	global_store_dwordx2 v[74:75], v[22:23], off offset:1024 nt
	v_pk_mul_f32 v[24:25], v[48:49], v[100:101] op_sel_hi:[1,0]
	v_pk_mul_f32 v[26:27], v[50:51], v[100:101] op_sel_hi:[1,0]
	v_pk_mul_f32 v[16:17], v[16:17], v[150:151]
	v_pk_mul_f32 v[18:19], v[18:19], v[152:153]
	v_pk_mul_f32 v[20:21], v[24:25], v[150:151]
	v_pk_mul_f32 v[22:23], v[26:27], v[152:153]
	v_cvt_pk_bf16_f32 v16, v16, v17
	v_cvt_pk_bf16_f32 v17, v18, v19
	v_cvt_pk_bf16_f32 v18, v20, v21
	v_cvt_pk_bf16_f32 v19, v22, v23
	global_store_dwordx2 v[70:71], v[16:17], off offset:1536 nt
	global_store_dwordx2 v[74:75], v[18:19], off offset:1536 nt
	v_pk_mul_f32 v[20:21], v[44:45], v[100:101] op_sel_hi:[1,0]
	v_pk_mul_f32 v[22:23], v[46:47], v[100:101] op_sel_hi:[1,0]
	v_pk_mul_f32 v[12:13], v[12:13], v[154:155]
	v_pk_mul_f32 v[14:15], v[14:15], v[156:157]
	v_pk_mul_f32 v[16:17], v[20:21], v[154:155]
	v_pk_mul_f32 v[18:19], v[22:23], v[156:157]
	v_cvt_pk_bf16_f32 v12, v12, v13
	v_cvt_pk_bf16_f32 v13, v14, v15
	v_cvt_pk_bf16_f32 v14, v16, v17
	v_cvt_pk_bf16_f32 v15, v18, v19
	global_store_dwordx2 v[70:71], v[12:13], off offset:2048 nt
	global_store_dwordx2 v[74:75], v[14:15], off offset:2048 nt
	v_pk_mul_f32 v[16:17], v[40:41], v[100:101] op_sel_hi:[1,0]
	v_pk_mul_f32 v[18:19], v[42:43], v[100:101] op_sel_hi:[1,0]
	v_pk_mul_f32 v[8:9], v[8:9], v[158:159]
	v_pk_mul_f32 v[10:11], v[10:11], v[160:161]
	v_pk_mul_f32 v[12:13], v[16:17], v[158:159]
	v_pk_mul_f32 v[14:15], v[18:19], v[160:161]
	v_cvt_pk_bf16_f32 v8, v8, v9
	v_cvt_pk_bf16_f32 v9, v10, v11
	v_cvt_pk_bf16_f32 v10, v12, v13
	v_cvt_pk_bf16_f32 v11, v14, v15
	global_store_dwordx2 v[70:71], v[8:9], off offset:2560 nt
	global_store_dwordx2 v[74:75], v[10:11], off offset:2560 nt
	v_pk_mul_f32 v[12:13], v[36:37], v[100:101] op_sel_hi:[1,0]
	v_pk_mul_f32 v[14:15], v[38:39], v[100:101] op_sel_hi:[1,0]
	v_pk_mul_f32 v[4:5], v[4:5], v[162:163]
	v_pk_mul_f32 v[6:7], v[6:7], v[164:165]
	v_pk_mul_f32 v[8:9], v[12:13], v[162:163]
	v_pk_mul_f32 v[10:11], v[14:15], v[164:165]
	v_cvt_pk_bf16_f32 v4, v4, v5
	v_cvt_pk_bf16_f32 v5, v6, v7
	v_cvt_pk_bf16_f32 v6, v8, v9
	v_cvt_pk_bf16_f32 v7, v10, v11
	global_store_dwordx2 v[70:71], v[4:5], off offset:3072 nt
	global_store_dwordx2 v[74:75], v[6:7], off offset:3072 nt
	v_pk_mul_f32 v[8:9], v[32:33], v[100:101] op_sel_hi:[1,0]
	v_pk_mul_f32 v[10:11], v[34:35], v[100:101] op_sel_hi:[1,0]
	v_pk_mul_f32 v[0:1], v[0:1], v[168:169]
	v_pk_mul_f32 v[2:3], v[2:3], v[170:171]
	v_pk_mul_f32 v[4:5], v[8:9], v[168:169]
	v_pk_mul_f32 v[6:7], v[10:11], v[170:171]
	v_cvt_pk_bf16_f32 v0, v0, v1
	v_cvt_pk_bf16_f32 v1, v2, v3
	v_cvt_pk_bf16_f32 v2, v4, v5
	v_cvt_pk_bf16_f32 v3, v6, v7
	global_store_dwordx2 v[70:71], v[0:1], off offset:3584 nt
	global_store_dwordx2 v[74:75], v[2:3], off offset:3584 nt
	v_lshl_add_u64 v[70:71], v[70:71], 0, s[8:9]
	s_cbranch_scc0 .LBB0_1300
	v_readlane_b32 s0, v245, 40
	s_add_i32 s0, s0, s82

; __device__ __forceinline__ void rms_row_f32(float* xrow, const float* g, int lane) {
;     f32x4 v[8]; float s = 0.f;
; #pragma unroll
;     for (int j = 0; j < 8; ++j) { v[j] = __builtin_nontemporal_load((const f32x4*)xrow + lane + 64 * j); s += (v[j][0] * v[j][0] + v[j][1] * v[j][1]) + (v[j][2] * v[j][2] + v[j][3] * v[j][3]); }
;     const float rstd = rsqrtf(wave_sum(s) * (1.f / D) + EPS);
; #pragma unroll
;     for (int j = 0; j < 8; ++j) { const f32x4 gg = ((const f32x4*)g)[lane + 64 * j]; __builtin_nontemporal_store(v[j] * rstd * gg, (f32x4*)xrow + lane + 64 * j); }
; __global__ void __launch_bounds__(NTHREADS, 2) fwd_kernel(Args args) {
;     ...
;     if (IN(17)) { for (int m = gw; m < T; m += NGW) rms_row_f32(out + (size_t)m * D, final_norm, lane); }
.LBB0_1509:
	s_cmp_lt_i32 s90, 18
	s_cselect_b64 s[0:1], -1, 0
	s_and_b64 s[0:1], s[0:1], s[2:3]
	s_cmp_lt_i32 s48, 0x8000
	s_cselect_b64 s[2:3], -1, 0
	s_and_b64 s[0:1], s[0:1], s[2:3]
	s_andn2_b64 vcc, exec, s[0:1]
	s_cbranch_vccnz .LBB0_1512
	v_mbcnt_lo_u32_b32 v0, -1, 0
	v_mbcnt_hi_u32_b32 v0, -1, v0
	v_and_b32_e32 v1, 64, v0
	v_add_u32_e32 v1, 64, v1
	v_xor_b32_e32 v2, 1, v0
	v_cmp_lt_i32_e32 vcc, v2, v1
	v_lshlrev_b32_e32 v10, 4, v176
	v_mov_b32_e32 v11, 0
	v_cndmask_b32_e32 v2, v0, v2, vcc
	v_lshlrev_b32_e32 v12, 2, v2
	v_xor_b32_e32 v2, 2, v0
	v_cmp_lt_i32_e32 vcc, v2, v1
	s_ashr_i32 s49, s48, 31
	s_mov_b64 s[0:1], 0x1000
	v_cndmask_b32_e32 v2, v0, v2, vcc
	v_lshlrev_b32_e32 v13, 2, v2
	v_xor_b32_e32 v2, 4, v0
	v_cmp_lt_i32_e32 vcc, v2, v1
	s_lshl_b64 s[2:3], s[48:49], 13
	s_add_u32 s2, s86, s2
	v_cndmask_b32_e32 v2, v0, v2, vcc
	v_lshlrev_b32_e32 v14, 2, v2
	v_xor_b32_e32 v2, 8, v0
	v_cmp_lt_i32_e32 vcc, v2, v1
	s_addc_u32 s3, s87, s3
	s_ashr_i32 s37, s36, 31
	v_cndmask_b32_e32 v2, v0, v2, vcc
	v_lshlrev_b32_e32 v15, 2, v2
	v_xor_b32_e32 v2, 16, v0
	v_cmp_lt_i32_e32 vcc, v2, v1
	v_mov_b32_e32 v18, 0x358637bd
	s_nop 0
	v_cndmask_b32_e32 v2, v0, v2, vcc
	v_lshlrev_b32_e32 v16, 2, v2
	v_xor_b32_e32 v2, 32, v0
	v_cmp_lt_i32_e32 vcc, v2, v1
	s_nop 1
	v_cndmask_b32_e32 v0, v0, v2, vcc
	v_lshlrev_b32_e32 v17, 2, v0
	v_lshl_add_u64 v[0:1], s[84:85], 0, v[10:11]
	v_lshl_add_u64 v[2:3], v[0:1], 0, s[0:1]
	s_mov_b64 s[0:1], 0x1400
	v_lshl_add_u64 v[4:5], v[0:1], 0, s[0:1]
	s_mov_b64 s[0:1], 0x1800
	v_lshl_add_u64 v[6:7], v[0:1], 0, s[0:1]
	s_mov_b64 s[0:1], 0x1c00
	v_lshl_add_u64 v[10:11], s[2:3], 0, v[10:11]
	v_lshl_add_u64 v[8:9], v[0:1], 0, s[0:1]
	v_lshl_add_u64 v[10:11], v[10:11], 0, s[0:1]
	s_lshl_b64 s[0:1], s[36:37], 13
	s_mov_b32 s2, 0x800000
	global_load_dwordx4 v[88:91], v[0:1], off
	global_load_dwordx4 v[92:95], v[0:1], off offset:1024
	global_load_dwordx4 v[96:99], v[0:1], off offset:2048
	global_load_dwordx4 v[100:103], v[0:1], off offset:3072
	global_load_dwordx4 v[104:107], v[2:3], off
	global_load_dwordx4 v[108:111], v[4:5], off
	global_load_dwordx4 v[112:115], v[6:7], off
	global_load_dwordx4 v[116:119], v[8:9], off
; __device__ __forceinline__ void rms_row_f32(float* xrow, const float* g, int lane) {
;     f32x4 v[8]; float s = 0.f;
; #pragma unroll
;     for (int j = 0; j < 8; ++j) { v[j] = __builtin_nontemporal_load((const f32x4*)xrow + lane + 64 * j); s += (v[j][0] * v[j][0] + v[j][1] * v[j][1]) + (v[j][2] * v[j][2] + v[j][3] * v[j][3]); }
;     const float rstd = rsqrtf(wave_sum(s) * (1.f / D) + EPS);
; #pragma unroll
;     for (int j = 0; j < 8; ++j) { const f32x4 gg = ((const f32x4*)g)[lane + 64 * j]; __builtin_nontemporal_store(v[j] * rstd * gg, (f32x4*)xrow + lane + 64 * j); }
.LBB0_1511:
	global_load_dwordx4 v[20:23], v[10:11], off offset:-3072 nt
	global_load_dwordx4 v[24:27], v[10:11], off offset:-2048 nt
	global_load_dwordx4 v[28:31], v[10:11], off nt
	global_load_dwordx4 v[32:35], v[10:11], off offset:-1024 nt
	v_add_co_u32_e32 v56, vcc, 0xfffff000, v10
	s_add_i32 s48, s48, s36
	s_nop 0
	v_addc_co_u32_e32 v57, vcc, -1, v11, vcc
	global_load_dwordx4 v[36:39], v[56:57], off offset:-3072 nt
	global_load_dwordx4 v[40:43], v[56:57], off offset:-2048 nt
	global_load_dwordx4 v[44:47], v[56:57], off offset:-1024 nt
	global_load_dwordx4 v[48:51], v[10:11], off offset:-4096 nt
	s_cmp_lt_i32 s48, 0x8000
	s_waitcnt vmcnt(0)
	v_mul_f32_e32 v81, v21, v21
	v_pk_mul_f32 v[58:59], v[26:27], v[26:27]
	v_pk_mul_f32 v[60:61], v[24:25], v[24:25]
	v_mul_f32_e32 v62, v33, v33
	v_mul_f32_e32 v64, v35, v35
	v_mul_f32_e32 v79, v30, v30
	v_mul_f32_e32 v86, v31, v31
	v_pk_mov_b32 v[66:67], v[60:61], v[58:59] op_sel:[1,0]
	v_mov_b32_e32 v61, v59
	v_pk_fma_f32 v[58:59], v[32:33], v[32:33], v[62:63] op_sel_hi:[1,1,0]
	v_pk_fma_f32 v[62:63], v[34:35], v[34:35], v[64:65] op_sel_hi:[1,1,0]
	v_mov_b32_e32 v68, v37
	v_mov_b32_e32 v69, v41
	v_mov_b32_e32 v72, v39
	v_mov_b32_e32 v73, v43
	v_mov_b32_e32 v64, v36
	v_mov_b32_e32 v65, v40
	v_mov_b32_e32 v70, v38
	v_mov_b32_e32 v71, v42
	v_pk_mul_f32 v[74:75], v[46:47], v[46:47]
	v_pk_mul_f32 v[76:77], v[44:45], v[44:45]
	v_pk_add_f32 v[60:61], v[66:67], v[60:61]
	v_mov_b32_e32 v59, v79
	v_mov_b32_e32 v63, v86
	v_pk_mul_f32 v[66:67], v[68:69], v[68:69]
	v_pk_mul_f32 v[68:69], v[72:73], v[72:73]
	v_pk_mov_b32 v[72:73], v[76:77], v[74:75] op_sel:[1,0]
	v_mov_b32_e32 v77, v75
	v_pk_add_f32 v[58:59], v[58:59], v[62:63]
	v_pk_fma_f32 v[62:63], v[64:65], v[64:65], v[66:67]
	v_pk_fma_f32 v[64:65], v[70:71], v[70:71], v[68:69]
	v_mul_f32_e32 v78, v49, v49
	v_mul_f32_e32 v80, v51, v51
	v_pk_add_f32 v[66:67], v[72:73], v[76:77]
	v_pk_add_f32 v[62:63], v[62:63], v[64:65]
	v_mul_f32_e32 v19, v20, v20
	v_mul_f32_e32 v82, v22, v22
	v_mul_f32_e32 v83, v23, v23
	v_pk_fma_f32 v[74:75], v[48:49], v[48:49], v[78:79] op_sel_hi:[1,1,0]
	v_pk_fma_f32 v[78:79], v[50:51], v[50:51], v[80:81] op_sel_hi:[1,1,0]
	v_pk_add_f32 v[64:65], v[66:67], v[66:67] op_sel:[0,1] op_sel_hi:[1,0]
	v_pk_add_f32 v[62:63], v[62:63], v[62:63] op_sel:[0,1] op_sel_hi:[1,0]
	v_mov_b32_e32 v75, v82
	v_mov_b32_e32 v79, v83
	v_mov_b32_e32 v65, v81
	v_mov_b32_e32 v63, v19
	v_pk_add_f32 v[66:67], v[74:75], v[78:79]
	v_pk_add_f32 v[62:63], v[62:63], v[64:65]
	v_mul_f32_e32 v84, v28, v28
	v_pk_add_f32 v[62:63], v[62:63], v[66:67]
	v_mul_f32_e32 v85, v29, v29
	v_pk_add_f32 v[60:61], v[60:61], v[60:61] op_sel:[0,1] op_sel_hi:[1,0]
	v_pk_add_f32 v[62:63], v[62:63], v[62:63] op_sel:[0,1] op_sel_hi:[1,0]
	v_mov_b32_e32 v61, v85
	v_mov_b32_e32 v63, v84
	v_pk_add_f32 v[60:61], v[62:63], v[60:61]
	s_nop 0
	v_pk_add_f32 v[58:59], v[60:61], v[58:59]
	s_nop 0
	v_add_f32_e32 v19, v58, v59
	ds_bpermute_b32 v58, v12, v19
	s_waitcnt lgkmcnt(0)
	v_add_f32_e32 v19, v19, v58
	ds_bpermute_b32 v58, v13, v19
	s_waitcnt lgkmcnt(0)
	v_add_f32_e32 v19, v19, v58
	ds_bpermute_b32 v58, v14, v19
	s_waitcnt lgkmcnt(0)
	v_add_f32_e32 v19, v19, v58
	ds_bpermute_b32 v58, v15, v19
	s_waitcnt lgkmcnt(0)
	v_add_f32_e32 v19, v19, v58
	ds_bpermute_b32 v58, v16, v19
	s_waitcnt lgkmcnt(0)
	v_add_f32_e32 v19, v19, v58
	ds_bpermute_b32 v58, v17, v19
	s_waitcnt lgkmcnt(0)
	v_add_f32_e32 v19, v19, v58
	v_fmamk_f32 v19, v19, 0x3a000000, v18
	v_mul_f32_e32 v58, 0x4b800000, v19
	v_cmp_gt_f32_e32 vcc, s2, v19
	s_nop 1
	v_cndmask_b32_e32 v19, v19, v58, vcc
	v_rsq_f32_e32 v19, v19
	s_nop 0
	v_mul_f32_e32 v58, 0x45800000, v19
	v_cndmask_b32_e32 v58, v19, v58, vcc
	v_pk_mul_f32 v[36:37], v[36:37], v[58:59] op_sel_hi:[1,0]
	v_pk_mul_f32 v[38:39], v[38:39], v[58:59] op_sel_hi:[1,0]
	v_pk_mul_f32 v[36:37], v[88:89], v[36:37]
	v_pk_mul_f32 v[38:39], v[90:91], v[38:39]
	global_store_dwordx4 v[56:57], v[36:39], off offset:-3072 nt
	v_pk_mul_f32 v[42:43], v[42:43], v[58:59] op_sel_hi:[1,0]
	v_pk_mul_f32 v[40:41], v[40:41], v[58:59] op_sel_hi:[1,0]
	v_pk_mul_f32 v[22:23], v[22:23], v[58:59] op_sel_hi:[1,0]
	v_pk_mul_f32 v[20:21], v[20:21], v[58:59] op_sel_hi:[1,0]
	v_pk_mul_f32 v[26:27], v[26:27], v[58:59] op_sel_hi:[1,0]
	v_pk_mul_f32 v[24:25], v[24:25], v[58:59] op_sel_hi:[1,0]
	v_pk_mul_f32 v[36:37], v[92:93], v[40:41]
	v_pk_mul_f32 v[38:39], v[94:95], v[42:43]
	global_store_dwordx4 v[56:57], v[36:39], off offset:-2048 nt
	v_pk_mul_f32 v[40:41], v[46:47], v[58:59] op_sel_hi:[1,0]
	v_pk_mul_f32 v[42:43], v[44:45], v[58:59] op_sel_hi:[1,0]
	v_pk_mul_f32 v[38:39], v[98:99], v[40:41]
	v_pk_mul_f32 v[36:37], v[96:97], v[42:43]
	global_store_dwordx4 v[56:57], v[36:39], off offset:-1024 nt
	v_pk_mul_f32 v[40:41], v[50:51], v[58:59] op_sel_hi:[1,0]
	v_pk_mul_f32 v[42:43], v[48:49], v[58:59] op_sel_hi:[1,0]
	v_pk_mul_f32 v[38:39], v[102:103], v[40:41]
	v_pk_mul_f32 v[36:37], v[100:101], v[42:43]
	global_store_dwordx4 v[10:11], v[36:39], off offset:-4096 nt
	v_pk_mul_f32 v[20:21], v[104:105], v[20:21]
	v_pk_mul_f32 v[22:23], v[106:107], v[22:23]
	global_store_dwordx4 v[10:11], v[20:23], off offset:-3072 nt
	s_nop 1
	v_pk_mul_f32 v[20:21], v[108:109], v[24:25]
	v_pk_mul_f32 v[22:23], v[110:111], v[26:27]
	global_store_dwordx4 v[10:11], v[20:23], off offset:-2048 nt
	v_pk_mul_f32 v[24:25], v[34:35], v[58:59] op_sel_hi:[1,0]
	v_pk_mul_f32 v[26:27], v[32:33], v[58:59] op_sel_hi:[1,0]
	v_pk_mul_f32 v[22:23], v[24:25], v[114:115]
	v_pk_mul_f32 v[20:21], v[26:27], v[112:113]
	global_store_dwordx4 v[10:11], v[20:23], off offset:-1024 nt
	v_pk_mul_f32 v[24:25], v[30:31], v[58:59] op_sel_hi:[1,0]
	v_pk_mul_f32 v[26:27], v[28:29], v[58:59] op_sel_hi:[1,0]
	v_pk_mul_f32 v[22:23], v[24:25], v[118:119]
	v_pk_mul_f32 v[20:21], v[26:27], v[116:117]
	global_store_dwordx4 v[10:11], v[20:23], off nt
	v_lshl_add_u64 v[10:11], v[10:11], 0, s[0:1]
	s_cbranch_scc1 .LBB0_1511
